# scan: output-stage LDS reads issued before the next-chunk staging writes, counted lgkmcnt waits
# baseline (speedup 1.0000x reference)
; DI unsigned cvt_pk_bf16(float lo, float hi) { unsigned r; asm volatile("v_cvt_pk_bf16_f32 %0, %1, %2" : "=v"(r) : "v"(lo), "v"(hi)); return r; }
; #define RT_LGKM(n) do { asm volatile("s_waitcnt lgkmcnt(" #n ")" ::: "memory"); __builtin_amdgcn_sched_barrier(0); } while (0)
; template <int FWD, class BarrierFn>
; DI void scan2_dir(const bf16_t* __restrict__ Qg, const bf16_t* __restrict__ Kg, bf16_t* Vg, bf16_t* Tg, bf16_t* TCB, float* stats, int b, int h, int sl, float lg, char* lds, const BarrierFn& gbar) {
;     ...
;             f32x4 s0 = {0.f, 0.f, 0.f, 0.f}, s1 = {0.f, 0.f, 0.f, 0.f};
;             bf16x8 ak[2], aq0[2], aq1[2], bk[2], bq0[2], bq1[2];
;     ...
;             ST_LOAD(ak, aq0, aq1, 0); ST_LOAD(bk, bq0, bq1, 2);
;             ST_MMA(ak, aq0, aq1); ST_LOAD(ak, aq0, aq1, 4);
;             ST_MMA(bk, bq0, bq1); ST_LOAD(bk, bq0, bq1, 6);
;             ST_MMA(ak, aq0, aq1); ST_MMA(bk, bq0, bq1);
;     ...
;             const int n0 = 16 * qt0 + c, n1 = n0 + 16, mb = 16 * kt + 4 * g;
;             float p0[4], p1[4];
; #pragma unroll
;             for (int jj = 0; jj < 4; ++jj) { const int m = mb + jj; const float wmv = wm[jj];
;                 const bool k0 = FWD ? (m <= n0) : (m > n0), k1 = FWD ? (m <= n1) : (m > n1);
;                 p0[jj] = k0 ? s0[jj] * wmv : 0.f; p1[jj] = k1 ? s1[jj] * wmv : 0.f; }
;             u32x2 w0 = {cvt_pk_bf16(p0[0], p0[1]), cvt_pk_bf16(p0[2], p0[3])}, w1 = {cvt_pk_bf16(p1[0], p1[1]), cvt_pk_bf16(p1[2], p1[3])};
;             *(u32x2*)(lds + P2_OFF + n0 * PRS + mb * 2) = w0; *(u32x2*)(lds + P2_OFF + n1 * PRS + mb * 2) = w1;
;         }
;         f32x4 o[4];
; #pragma unroll
;         for (int nt = 0; nt < 4; ++nt) o[nt] = (f32x4){0.f, 0.f, 0.f, 0.f};
;         {
;             bf16x8 qa[4], qb[4];
;     ...
;             qs_load<0>(qa, qs_b); qs_load<1>(qb, qs_b);
;             RT_LGKM(8); QS_MMA(qa, 0); qs_load<2>(qa, qs_b);
;             RT_LGKM(8); QS_MMA(qb, 1); qs_load<3>(qb, qs_b);
;             RT_LGKM(8); QS_MMA(qa, 2); qs_load<4>(qa, qs_b);
;             RT_LGKM(8); QS_MMA(qb, 3); qs_load<5>(qb, qs_b);
;             RT_LGKM(8); QS_MMA(qa, 4); qs_load<6>(qa, qs_b);
;             RT_LGKM(8); QS_MMA(qb, 5); qs_load<7>(qb, qs_b);
;             RT_LGKM(8); QS_MMA(qa, 6);
;             RT_LGKM(0); QS_MMA(qb, 7);
.LBB0_362:
	ds_read_b128 v[112:115], v214 offset:33792
	ds_read_b128 v[116:119], v214 offset:33856
	ds_read_b128 v[120:123], v215
	ds_read_b128 v[124:127], v215 offset:64
	ds_read_b128 v[128:131], v215 offset:8448
	ds_read_b128 v[132:135], v215 offset:8512
	ds_read_b128 v[136:139], v214 offset:33920
	ds_read_b128 v[140:143], v214 offset:33984
	ds_read_b128 v[218:221], v215 offset:128
	ds_read_b128 v[232:235], v215 offset:192
	ds_read_b128 v[236:239], v215 offset:8576
	ds_read_b128 v[240:243], v215 offset:8640
	s_waitcnt lgkmcnt(9)
	v_mfma_f32_16x16x32_bf16 v[120:123], v[112:115], v[120:123], 0
	s_waitcnt lgkmcnt(7)
	v_mfma_f32_16x16x32_bf16 v[112:115], v[112:115], v[128:131], 0
	ds_read_b128 v[128:131], v214 offset:34048
	ds_read_b128 v[244:247], v214 offset:34112
	ds_read_b128 v[248:251], v215 offset:256
	ds_read_b128 v[222:225], v215 offset:320
	v_mfma_f32_16x16x32_bf16 v[120:123], v[116:119], v[124:127], v[120:123]
	ds_read_b128 v[124:127], v215 offset:8704
	ds_read_b128 v[226:229], v215 offset:8768
	s_waitcnt lgkmcnt(12)
	v_mfma_f32_16x16x32_bf16 v[112:115], v[116:119], v[132:135], v[112:115]
	s_waitcnt lgkmcnt(9)
	v_mfma_f32_16x16x32_bf16 v[116:119], v[136:139], v[218:221], v[120:123]
	s_waitcnt lgkmcnt(7)
	v_mfma_f32_16x16x32_bf16 v[112:115], v[136:139], v[236:239], v[112:115]
	s_nop 0
	ds_read_b128 v[120:123], v214 offset:34176
	ds_read_b128 v[132:135], v214 offset:34240
	ds_read_b128 v[136:139], v215 offset:384
	ds_read_b128 v[218:221], v215 offset:448
	v_mfma_f32_16x16x32_bf16 v[116:119], v[140:143], v[232:235], v[116:119]
	ds_read_b128 v[232:235], v215 offset:8832
	ds_read_b128 v[236:239], v215 offset:8896
	s_waitcnt lgkmcnt(12)
	v_mfma_f32_16x16x32_bf16 v[112:115], v[140:143], v[240:243], v[112:115]
	s_waitcnt lgkmcnt(9)
	v_mfma_f32_16x16x32_bf16 v[116:119], v[128:131], v[248:251], v[116:119]
	s_waitcnt lgkmcnt(7)
	v_mfma_f32_16x16x32_bf16 v[112:115], v[128:131], v[124:127], v[112:115]
	v_mfma_f32_16x16x32_bf16 v[116:119], v[244:247], v[222:225], v[116:119]
	s_waitcnt lgkmcnt(6)
	v_mfma_f32_16x16x32_bf16 v[112:115], v[244:247], v[226:229], v[112:115]
	s_waitcnt lgkmcnt(3)
	v_mfma_f32_16x16x32_bf16 v[116:119], v[120:123], v[136:139], v[116:119]
	s_waitcnt lgkmcnt(1)
	v_mfma_f32_16x16x32_bf16 v[112:115], v[120:123], v[232:235], v[112:115]
	v_mfma_f32_16x16x32_bf16 v[116:119], v[132:135], v[218:221], v[116:119]
	s_waitcnt lgkmcnt(0)
	v_mfma_f32_16x16x32_bf16 v[112:115], v[132:135], v[236:239], v[112:115]
	s_nop 7
	v_mul_f32_e32 v112, v169, v112
	v_mul_f32_e32 v113, v170, v113
	v_mul_f32_e32 v116, v169, v116
	v_cndmask_b32_e64 v120, v112, 0, s[8:9]
	v_mul_f32_e32 v112, v170, v117
	v_cndmask_b32_e64 v117, 0, v113, s[12:13]
	v_mul_f32_e32 v113, v171, v118
	v_mul_f32_e32 v114, v171, v114
	v_cndmask_b32_e64 v116, v116, 0, s[6:7]
	v_cndmask_b32_e64 v112, 0, v112, s[10:11]
	v_cndmask_b32_e64 v113, v113, 0, s[14:15]
	v_cndmask_b32_e64 v118, v114, 0, s[16:17]
	v_mul_f32_e32 v114, v172, v119
	v_mul_f32_e32 v115, v172, v115
	v_cndmask_b32_e64 v114, v114, 0, s[18:19]
	v_cndmask_b32_e64 v115, v115, 0, s[20:21]
	v_cvt_pk_bf16_f32 v112, v116, v112
	v_cvt_pk_bf16_f32 v113, v113, v114
	v_add_u32_e32 v116, v212, v213
	v_cvt_pk_bf16_f32 v114, v120, v117
	v_cvt_pk_bf16_f32 v115, v118, v115
	ds_write_b64 v116, v[112:113]
	ds_write_b64 v216, v[114:115]
	ds_read_b64 v[112:113], v199 offset:0
	ds_read_b64 v[114:115], v199 offset:32
	ds_read_b64 v[116:117], v199 offset:0x2100
	ds_read_b64 v[118:119], v199 offset:0x2120
	ds_read_b64 v[120:121], v199 offset:0x4200
	ds_read_b64 v[122:123], v199 offset:0x4220
	ds_read_b64 v[124:125], v199 offset:0x6300
	ds_read_b64 v[126:127], v199 offset:0x6320
	ds_read_b64 v[128:129], v199 offset:64
	ds_read_b64 v[130:131], v199 offset:0x60
	ds_read_b64 v[132:133], v199 offset:0x2140
	ds_read_b64 v[134:135], v199 offset:0x2160
	ds_read_b64 v[136:137], v199 offset:0x4240
	ds_read_b64 v[138:139], v199 offset:0x4260
	ds_read_b64 v[140:141], v199 offset:0x6340
	ds_read_b64 v[142:143], v199 offset:0x6360
	s_waitcnt lgkmcnt(8)
	v_cvt_pk_bf16_f32 v218, v40, v41
	v_cvt_pk_bf16_f32 v219, v42, v43
	v_cvt_pk_bf16_f32 v220, v44, v45
	v_cvt_pk_bf16_f32 v221, v46, v47
	s_nop 0
	v_mfma_f32_16x16x32_bf16 v[112:115], v[112:115], v[218:221], 0
	v_mfma_f32_16x16x32_bf16 v[116:119], v[116:119], v[218:221], 0
	v_mfma_f32_16x16x32_bf16 v[120:123], v[120:123], v[218:221], 0
	v_mfma_f32_16x16x32_bf16 v[124:127], v[124:127], v[218:221], 0
	ds_read_b64 v[218:219], v199 offset:0x80
	ds_read_b64 v[220:221], v199 offset:0xa0
	ds_read_b64 v[222:223], v199 offset:0x2180
	ds_read_b64 v[224:225], v199 offset:0x21a0
	ds_read_b64 v[226:227], v199 offset:0x4280
	ds_read_b64 v[228:229], v199 offset:0x42a0
	ds_read_b64 v[232:233], v199 offset:0x6380
	ds_read_b64 v[234:235], v199 offset:0x63a0
	s_waitcnt lgkmcnt(8)
	v_cvt_pk_bf16_f32 v236, v52, v53
	v_cvt_pk_bf16_f32 v237, v54, v55
	v_cvt_pk_bf16_f32 v238, v48, v49
	v_cvt_pk_bf16_f32 v239, v50, v51
	s_nop 0
	v_mfma_f32_16x16x32_bf16 v[112:115], v[128:131], v[236:239], v[112:115]
	ds_read_b64 v[128:129], v199 offset:0xc0
	ds_read_b64 v[130:131], v199 offset:0xe0
	v_mfma_f32_16x16x32_bf16 v[116:119], v[132:135], v[236:239], v[116:119]
	ds_read_b64 v[132:133], v199 offset:0x21c0
	ds_read_b64 v[134:135], v199 offset:0x21e0
	v_mfma_f32_16x16x32_bf16 v[120:123], v[136:139], v[236:239], v[120:123]
	ds_read_b64 v[136:137], v199 offset:0x42c0
	ds_read_b64 v[138:139], v199 offset:0x42e0
	v_mfma_f32_16x16x32_bf16 v[124:127], v[140:143], v[236:239], v[124:127]
	ds_read_b64 v[140:141], v199 offset:0x63c0
	ds_read_b64 v[142:143], v199 offset:0x63e0
	s_waitcnt lgkmcnt(8)
; template <int OFF> DI s16x4 tr_rd(unsigned addr) { s16x4 r; asm volatile("ds_read_b64_tr_b16 %0, %1 offset:%2" : "=&v"(r) : "v"(addr), "i"(OFF) : "memory"); return r; }
; #define RT_LGKM(n) do { asm volatile("s_waitcnt lgkmcnt(" #n ")" ::: "memory"); __builtin_amdgcn_sched_barrier(0); } while (0)
; template <int FWD, class BarrierFn>
; DI void scan2_dir(const bf16_t* __restrict__ Qg, const bf16_t* __restrict__ Kg, bf16_t* Vg, bf16_t* Tg, bf16_t* TCB, float* stats, int b, int h, int sl, float lg, char* lds, const BarrierFn& gbar) {
;     ...
;             qs_load<0>(qa, qs_b); qs_load<1>(qb, qs_b);
;             RT_LGKM(8); QS_MMA(qa, 0); qs_load<2>(qa, qs_b);
;             RT_LGKM(8); QS_MMA(qb, 1); qs_load<3>(qb, qs_b);
;             RT_LGKM(8); QS_MMA(qa, 2); qs_load<4>(qa, qs_b);
;             RT_LGKM(8); QS_MMA(qb, 3); qs_load<5>(qb, qs_b);
;             RT_LGKM(8); QS_MMA(qa, 4); qs_load<6>(qa, qs_b);
;             RT_LGKM(8); QS_MMA(qb, 5); qs_load<7>(qb, qs_b);
;             RT_LGKM(8); QS_MMA(qa, 6);
;             RT_LGKM(0); QS_MMA(qb, 7);
;     ...
;         }
;         bf16x8 vf0, vf1;
;         {
;             const s16x4 l0 = tr_rd<0>(vb_tr), h0 = tr_rd<8 * V2RS>(vb_tr), l1 = tr_rd<32 * V2RS>(vb_tr), h1 = tr_rd<40 * V2RS>(vb_tr);
;             KT8 ka, kb2;
;             kt_load<0>(ka, kb_tr);
	v_cvt_pk_bf16_f32 v236, v60, v61
	v_cvt_pk_bf16_f32 v237, v62, v63
	v_cvt_pk_bf16_f32 v238, v56, v57
	v_cvt_pk_bf16_f32 v239, v58, v59
	s_nop 0
	v_mfma_f32_16x16x32_bf16 v[112:115], v[218:221], v[236:239], v[112:115]
	ds_read_b64 v[218:219], v199 offset:0x100
	ds_read_b64 v[220:221], v199 offset:0x120
	v_mfma_f32_16x16x32_bf16 v[116:119], v[222:225], v[236:239], v[116:119]
	ds_read_b64 v[222:223], v199 offset:0x2200
	ds_read_b64 v[224:225], v199 offset:0x2220
	v_mfma_f32_16x16x32_bf16 v[120:123], v[226:229], v[236:239], v[120:123]
	ds_read_b64 v[226:227], v199 offset:0x4300
	ds_read_b64 v[228:229], v199 offset:0x4320
	v_mfma_f32_16x16x32_bf16 v[124:127], v[232:235], v[236:239], v[124:127]
	ds_read_b64 v[232:233], v199 offset:0x6400
	ds_read_b64 v[234:235], v199 offset:0x6420
	s_waitcnt lgkmcnt(8)
	v_cvt_pk_bf16_f32 v236, v68, v69
	v_cvt_pk_bf16_f32 v237, v70, v71
	v_cvt_pk_bf16_f32 v238, v64, v65
	v_cvt_pk_bf16_f32 v239, v66, v67
	s_nop 0
	v_mfma_f32_16x16x32_bf16 v[112:115], v[128:131], v[236:239], v[112:115]
	ds_read_b64 v[128:129], v199 offset:0x140
	ds_read_b64 v[130:131], v199 offset:0x160
	v_mfma_f32_16x16x32_bf16 v[116:119], v[132:135], v[236:239], v[116:119]
	ds_read_b64 v[132:133], v199 offset:0x2240
	ds_read_b64 v[134:135], v199 offset:0x2260
	v_mfma_f32_16x16x32_bf16 v[120:123], v[136:139], v[236:239], v[120:123]
	ds_read_b64 v[136:137], v199 offset:0x4340
	ds_read_b64 v[138:139], v199 offset:0x4360
	v_mfma_f32_16x16x32_bf16 v[124:127], v[140:143], v[236:239], v[124:127]
	ds_read_b64 v[140:141], v199 offset:0x6440
	ds_read_b64 v[142:143], v199 offset:0x6460
	s_waitcnt lgkmcnt(8)
	v_cvt_pk_bf16_f32 v236, v76, v77
	v_cvt_pk_bf16_f32 v237, v78, v79
	v_cvt_pk_bf16_f32 v238, v72, v73
	v_cvt_pk_bf16_f32 v239, v74, v75
	s_nop 0
	v_mfma_f32_16x16x32_bf16 v[112:115], v[218:221], v[236:239], v[112:115]
	ds_read_b64 v[218:219], v199 offset:0x180
	ds_read_b64 v[220:221], v199 offset:0x1a0
	v_mfma_f32_16x16x32_bf16 v[116:119], v[222:225], v[236:239], v[116:119]
	ds_read_b64 v[222:223], v199 offset:0x2280
	ds_read_b64 v[224:225], v199 offset:0x22a0
	v_mfma_f32_16x16x32_bf16 v[120:123], v[226:229], v[236:239], v[120:123]
	ds_read_b64 v[226:227], v199 offset:0x4380
	ds_read_b64 v[228:229], v199 offset:0x43a0
	v_mfma_f32_16x16x32_bf16 v[124:127], v[232:235], v[236:239], v[124:127]
	ds_read_b64 v[232:233], v199 offset:0x6480
	ds_read_b64 v[234:235], v199 offset:0x64a0
	s_waitcnt lgkmcnt(8)
	v_cvt_pk_bf16_f32 v236, v84, v85
	v_cvt_pk_bf16_f32 v237, v86, v87
	v_cvt_pk_bf16_f32 v238, v80, v81
	v_cvt_pk_bf16_f32 v239, v82, v83
	s_nop 0
	v_mfma_f32_16x16x32_bf16 v[112:115], v[128:131], v[236:239], v[112:115]
	ds_read_b64 v[128:129], v199 offset:0x1c0
	ds_read_b64 v[130:131], v199 offset:0x1e0
	v_mfma_f32_16x16x32_bf16 v[120:123], v[136:139], v[236:239], v[120:123]
	ds_read_b64 v[136:137], v199 offset:0x22c0
	ds_read_b64 v[138:139], v199 offset:0x22e0
	v_mfma_f32_16x16x32_bf16 v[124:127], v[140:143], v[236:239], v[124:127]
	ds_read_b64 v[140:141], v199 offset:0x43c0
	ds_read_b64 v[142:143], v199 offset:0x43e0
	v_mfma_f32_16x16x32_bf16 v[116:119], v[132:135], v[236:239], v[116:119]
	ds_read_b64 v[236:237], v199 offset:0x64c0
	ds_read_b64 v[238:239], v199 offset:0x64e0
	s_waitcnt lgkmcnt(8)
	v_cvt_pk_bf16_f32 v132, v92, v93
	v_cvt_pk_bf16_f32 v133, v94, v95
	v_cvt_pk_bf16_f32 v134, v100, v101
	v_cvt_pk_bf16_f32 v135, v102, v103
	s_waitcnt lgkmcnt(0)
	s_nop 0
	v_mfma_f32_16x16x32_bf16 v[112:115], v[218:221], v[132:135], v[112:115]
	v_mfma_f32_16x16x32_bf16 v[116:119], v[222:225], v[132:135], v[116:119]
	v_mfma_f32_16x16x32_bf16 v[120:123], v[226:229], v[132:135], v[120:123]
	v_mfma_f32_16x16x32_bf16 v[124:127], v[232:235], v[132:135], v[124:127]
	v_cvt_pk_bf16_f32 v218, v96, v97
	v_cvt_pk_bf16_f32 v219, v98, v99
	v_cvt_pk_bf16_f32 v220, v88, v89
	v_cvt_pk_bf16_f32 v221, v90, v91
	s_nop 0
	v_mfma_f32_16x16x32_bf16 v[132:135], v[128:131], v[218:221], v[112:115]
	v_mfma_f32_16x16x32_bf16 v[128:131], v[136:139], v[218:221], v[116:119]
	v_mfma_f32_16x16x32_bf16 v[116:119], v[140:143], v[218:221], v[120:123]
	ds_read_b64_tr_b16 v[120:121], v198 offset:0
	ds_read_b64_tr_b16 v[122:123], v198 offset:0x900
	v_mfma_f32_16x16x32_bf16 v[112:115], v[236:239], v[218:221], v[124:127]
	ds_read_b64_tr_b16 v[124:125], v198 offset:0x2400
	ds_read_b64_tr_b16 v[126:127], v198 offset:0x2d00
	ds_read_b64_tr_b16 v[218:219], v168 offset:0
	ds_read_b64_tr_b16 v[220:221], v168 offset:0x1100
	ds_read_b64_tr_b16 v[222:223], v168 offset:0x4400
	ds_read_b64_tr_b16 v[224:225], v168 offset:0x5500
	ds_read_b64_tr_b16 v[226:227], v168 offset:32
	ds_read_b64_tr_b16 v[228:229], v168 offset:0x1120
	ds_read_b64_tr_b16 v[232:233], v168 offset:0x4420
	ds_read_b64_tr_b16 v[234:235], v168 offset:0x5520
	s_waitcnt lgkmcnt(8)
; DI unsigned cvt_pk_bf16(float lo, float hi) { unsigned r; asm volatile("v_cvt_pk_bf16_f32 %0, %1, %2" : "=v"(r) : "v"(lo), "v"(hi)); return r; }
; DI float bf2f(bf16_t b) { return __uint_as_float(((unsigned)b) << 16); }
; template <int OFF> DI s16x4 tr_rd(unsigned addr) { s16x4 r; asm volatile("ds_read_b64_tr_b16 %0, %1 offset:%2" : "=&v"(r) : "v"(addr), "i"(OFF) : "memory"); return r; }
; DI bf16x8 cat(s16x4 l, s16x4 h) { return (bf16x8){l[0], l[1], l[2], l[3], h[0], h[1], h[2], h[3]}; }
; #define RT_LGKM(n) do { asm volatile("s_waitcnt lgkmcnt(" #n ")" ::: "memory"); __builtin_amdgcn_sched_barrier(0); } while (0)
; template <int FWD, class BarrierFn>
; DI void scan2_dir(const bf16_t* __restrict__ Qg, const bf16_t* __restrict__ Kg, bf16_t* Vg, bf16_t* Tg, bf16_t* TCB, float* stats, int b, int h, int sl, float lg, char* lds, const BarrierFn& gbar) {
;     ...
;             const s16x4 l0 = tr_rd<0>(vb_tr), h0 = tr_rd<8 * V2RS>(vb_tr), l1 = tr_rd<32 * V2RS>(vb_tr), h1 = tr_rd<40 * V2RS>(vb_tr);
;             KT8 ka, kb2;
;             kt_load<0>(ka, kb_tr);
;             RT_LGKM(8);
;             vf0 = cat(l0, h0); vf1 = cat(l1, h1);
;             bf16x8 vz0, vz1;
;             {
;                 float f[8];
; #pragma unroll
;                 for (int jj = 0; jj < 8; ++jj) f[jj] = bf2f((bf16_t)vf0[jj]) * zt0[jj];
;                 u32x4 w = {cvt_pk_bf16(f[0], f[1]), cvt_pk_bf16(f[2], f[3]), cvt_pk_bf16(f[4], f[5]), cvt_pk_bf16(f[6], f[7])};
;                 vz0 = *reinterpret_cast<bf16x8*>(&w);
; #pragma unroll
;                 for (int jj = 0; jj < 8; ++jj) f[jj] = bf2f((bf16_t)vf1[jj]) * zt1[jj];
;                 u32x4 w2 = {cvt_pk_bf16(f[0], f[1]), cvt_pk_bf16(f[2], f[3]), cvt_pk_bf16(f[4], f[5]), cvt_pk_bf16(f[6], f[7])};
;                 vz1 = *reinterpret_cast<bf16x8*>(&w2);
;             }
; #pragma unroll
;             for (int t = 0; t < 16; ++t) st[t] = st[t] * gC;
;             kt_load<2>(kb2, kb_tr);  RT_LGKM(8); kt_mma(st[0], st[1], ka, vz0, vz1);
;             kt_load<4>(ka, kb_tr);   RT_LGKM(8); kt_mma(st[2], st[3], kb2, vz0, vz1);
;             kt_load<6>(kb2, kb_tr);  RT_LGKM(8); kt_mma(st[4], st[5], ka, vz0, vz1);
;             kt_load<8>(ka, kb_tr);   RT_LGKM(8); kt_mma(st[6], st[7], kb2, vz0, vz1);
	s_nop 1
	v_lshlrev_b32_e32 v136, 16, v120
	v_and_b32_e32 v137, 0xffff0000, v120
	v_lshlrev_b32_e32 v138, 16, v121
	v_and_b32_e32 v139, 0xffff0000, v121
	v_lshlrev_b32_e32 v140, 16, v122
	v_and_b32_e32 v141, 0xffff0000, v122
	v_lshlrev_b32_e32 v142, 16, v123
	v_and_b32_e32 v143, 0xffff0000, v123
	v_mul_f32_e32 v136, v173, v136
	v_mul_f32_e32 v137, v175, v137
	v_mul_f32_e32 v138, v177, v138
	v_mul_f32_e32 v139, v179, v139
	v_mul_f32_e32 v140, v185, v140
	v_mul_f32_e32 v141, v187, v141
	v_mul_f32_e32 v142, v189, v142
	v_mul_f32_e32 v143, v191, v143
	v_cvt_pk_bf16_f32 v136, v136, v137
	v_cvt_pk_bf16_f32 v137, v138, v139
	v_cvt_pk_bf16_f32 v138, v140, v141
	v_cvt_pk_bf16_f32 v139, v142, v143
	v_lshlrev_b32_e32 v140, 16, v124
	v_and_b32_e32 v141, 0xffff0000, v124
	v_lshlrev_b32_e32 v142, 16, v125
	v_and_b32_e32 v143, 0xffff0000, v125
	v_and_b32_e32 v236, 0xffff0000, v127
	v_mul_f32_e32 v140, v174, v140
	v_mul_f32_e32 v141, v176, v141
	v_mul_f32_e32 v142, v178, v142
	v_mul_f32_e32 v143, v184, v143
	v_lshlrev_b32_e32 v159, 16, v126
	v_and_b32_e32 v180, 0xffff0000, v126
	v_lshlrev_b32_e32 v231, 16, v127
	v_mul_f32_e32 v236, v197, v236
	v_mul_f32_e32 v159, v186, v159
	v_mul_f32_e32 v180, v188, v180
	v_mul_f32_e32 v231, v190, v231
	v_cvt_pk_bf16_f32 v140, v140, v141
	v_cvt_pk_bf16_f32 v141, v142, v143
	v_cvt_pk_bf16_f32 v142, v159, v180
	v_cvt_pk_bf16_f32 v143, v231, v236
	ds_read_b64_tr_b16 v[236:237], v168 offset:64
	ds_read_b64_tr_b16 v[238:239], v168 offset:0x1140
	ds_read_b64_tr_b16 v[240:241], v168 offset:0x4440
	ds_read_b64_tr_b16 v[242:243], v168 offset:0x5540
	ds_read_b64_tr_b16 v[244:245], v168 offset:0x60
	ds_read_b64_tr_b16 v[246:247], v168 offset:0x1160
	ds_read_b64_tr_b16 v[248:249], v168 offset:0x4460
	ds_read_b64_tr_b16 v[250:251], v168 offset:0x5560
	s_waitcnt lgkmcnt(8)
	v_mov_b32_e32 v159, v158
	v_mul_f32_e32 v42, v158, v42
	v_mul_f32_e32 v43, v159, v43
	v_mul_f32_e32 v40, v160, v40
	v_mul_f32_e32 v41, v161, v41
	v_mul_f32_e32 v46, v158, v46
	v_mul_f32_e32 v47, v159, v47
	v_mul_f32_e32 v44, v160, v44
	v_mul_f32_e32 v45, v161, v45
	v_mfma_f32_16x16x32_bf16 v[40:43], v[218:221], v[136:139], v[40:43]
	v_mul_f32_e32 v54, v158, v54
	v_mul_f32_e32 v55, v159, v55
	v_mul_f32_e32 v52, v160, v52
	v_mul_f32_e32 v53, v161, v53
	v_mul_f32_e32 v50, v158, v50
	v_mul_f32_e32 v51, v159, v51
	v_mul_f32_e32 v48, v160, v48
	v_mul_f32_e32 v49, v161, v49
	ds_read_b64_tr_b16 v[218:219], v168 offset:0x80
	ds_read_b64_tr_b16 v[220:221], v168 offset:0x1180
	v_mfma_f32_16x16x32_bf16 v[40:43], v[222:225], v[140:143], v[40:43]
	ds_read_b64_tr_b16 v[222:223], v168 offset:0x4480
	ds_read_b64_tr_b16 v[224:225], v168 offset:0x5580
	v_mfma_f32_16x16x32_bf16 v[44:47], v[226:229], v[136:139], v[44:47]
	ds_read_b64_tr_b16 v[226:227], v168 offset:0xa0
	ds_read_b64_tr_b16 v[228:229], v168 offset:0x11a0
	v_mfma_f32_16x16x32_bf16 v[44:47], v[232:235], v[140:143], v[44:47]
	ds_read_b64_tr_b16 v[232:233], v168 offset:0x44a0
	ds_read_b64_tr_b16 v[234:235], v168 offset:0x55a0
	s_waitcnt lgkmcnt(8)
	v_mfma_f32_16x16x32_bf16 v[52:55], v[236:239], v[136:139], v[52:55]
	v_mul_f32_e32 v62, v158, v62
	v_mul_f32_e32 v63, v159, v63
	v_mul_f32_e32 v60, v160, v60
	v_mul_f32_e32 v61, v161, v61
	v_mul_f32_e32 v58, v158, v58
	v_mul_f32_e32 v59, v159, v59
	v_mul_f32_e32 v56, v160, v56
	v_mul_f32_e32 v57, v161, v57
	ds_read_b64_tr_b16 v[236:237], v168 offset:0xc0
	ds_read_b64_tr_b16 v[238:239], v168 offset:0x11c0
	v_mfma_f32_16x16x32_bf16 v[52:55], v[240:243], v[140:143], v[52:55]
	ds_read_b64_tr_b16 v[240:241], v168 offset:0x44c0
	ds_read_b64_tr_b16 v[242:243], v168 offset:0x55c0
	v_mfma_f32_16x16x32_bf16 v[48:51], v[244:247], v[136:139], v[48:51]
	ds_read_b64_tr_b16 v[244:245], v168 offset:0xe0
	ds_read_b64_tr_b16 v[246:247], v168 offset:0x11e0
	v_mfma_f32_16x16x32_bf16 v[48:51], v[248:251], v[140:143], v[48:51]
	ds_read_b64_tr_b16 v[248:249], v168 offset:0x44e0
	ds_read_b64_tr_b16 v[250:251], v168 offset:0x55e0
	s_waitcnt lgkmcnt(8)
	v_mfma_f32_16x16x32_bf16 v[60:63], v[218:221], v[136:139], v[60:63]
	v_mul_f32_e32 v70, v158, v70
	v_mul_f32_e32 v71, v159, v71
	v_mul_f32_e32 v68, v160, v68
	v_mul_f32_e32 v69, v161, v69
	v_mul_f32_e32 v66, v158, v66
	v_mul_f32_e32 v67, v159, v67
	v_mul_f32_e32 v64, v160, v64
	v_mul_f32_e32 v65, v161, v65
	ds_read_b64_tr_b16 v[218:219], v168 offset:0x100
	ds_read_b64_tr_b16 v[220:221], v168 offset:0x1200
	v_mfma_f32_16x16x32_bf16 v[60:63], v[222:225], v[140:143], v[60:63]
	ds_read_b64_tr_b16 v[222:223], v168 offset:0x4500
	ds_read_b64_tr_b16 v[224:225], v168 offset:0x5600
	v_mfma_f32_16x16x32_bf16 v[56:59], v[226:229], v[136:139], v[56:59]
	ds_read_b64_tr_b16 v[226:227], v168 offset:0x120
	ds_read_b64_tr_b16 v[228:229], v168 offset:0x1220
	v_mfma_f32_16x16x32_bf16 v[56:59], v[232:235], v[140:143], v[56:59]
	ds_read_b64_tr_b16 v[232:233], v168 offset:0x4520
	ds_read_b64_tr_b16 v[234:235], v168 offset:0x5620
	s_waitcnt lgkmcnt(8)
	v_mfma_f32_16x16x32_bf16 v[68:71], v[236:239], v[136:139], v[68:71]
	v_mul_f32_e32 v78, v158, v78
	v_mul_f32_e32 v79, v159, v79
	v_mul_f32_e32 v76, v160, v76
	v_mul_f32_e32 v77, v161, v77
	v_mul_f32_e32 v74, v158, v74
	v_mul_f32_e32 v75, v159, v75
	v_mul_f32_e32 v72, v160, v72
	v_mul_f32_e32 v73, v161, v73
	ds_read_b64_tr_b16 v[236:237], v168 offset:0x140
	ds_read_b64_tr_b16 v[238:239], v168 offset:0x1240
	v_mfma_f32_16x16x32_bf16 v[68:71], v[240:243], v[140:143], v[68:71]
	ds_read_b64_tr_b16 v[240:241], v168 offset:0x4540
	ds_read_b64_tr_b16 v[242:243], v168 offset:0x5640
	v_mfma_f32_16x16x32_bf16 v[64:67], v[244:247], v[136:139], v[64:67]
	ds_read_b64_tr_b16 v[244:245], v168 offset:0x160
	ds_read_b64_tr_b16 v[246:247], v168 offset:0x1260
	v_mfma_f32_16x16x32_bf16 v[64:67], v[248:251], v[140:143], v[64:67]
	ds_read_b64_tr_b16 v[248:249], v168 offset:0x4560
	ds_read_b64_tr_b16 v[250:251], v168 offset:0x5660
	s_waitcnt lgkmcnt(8)
; #define MFMA16(a, b, c) __builtin_amdgcn_mfma_f32_16x16x32_bf16((a), (b), (c), 0, 0, 0)
; #define RT_CB() do { asm volatile("" ::: "memory"); __builtin_amdgcn_sched_barrier(0); } while (0)
; #define RT_LGKM(n) do { asm volatile("s_waitcnt lgkmcnt(" #n ")" ::: "memory"); __builtin_amdgcn_sched_barrier(0); } while (0)
; template <int FWD, class BarrierFn>
; DI void scan2_dir(const bf16_t* __restrict__ Qg, const bf16_t* __restrict__ Kg, bf16_t* Vg, bf16_t* Tg, bf16_t* TCB, float* stats, int b, int h, int sl, float lg, char* lds, const BarrierFn& gbar) {
;     ...
;             kt_load<2>(kb2, kb_tr);  RT_LGKM(8); kt_mma(st[0], st[1], ka, vz0, vz1);
;             kt_load<4>(ka, kb_tr);   RT_LGKM(8); kt_mma(st[2], st[3], kb2, vz0, vz1);
;             kt_load<6>(kb2, kb_tr);  RT_LGKM(8); kt_mma(st[4], st[5], ka, vz0, vz1);
;             kt_load<8>(ka, kb_tr);   RT_LGKM(8); kt_mma(st[6], st[7], kb2, vz0, vz1);
;             kt_load<10>(kb2, kb_tr); RT_LGKM(8); kt_mma(st[8], st[9], ka, vz0, vz1);
;             kt_load<12>(ka, kb_tr);  RT_LGKM(8); kt_mma(st[10], st[11], kb2, vz0, vz1);
;             kt_load<14>(kb2, kb_tr); RT_LGKM(8); kt_mma(st[12], st[13], ka, vz0, vz1);
;             RT_LGKM(0); kt_mma(st[14], st[15], kb2, vz0, vz1);
;         }
;         __syncthreads();
;         {
;             bf16x8 pa[4], pb[4];
; #pragma unroll
;             for (int nt = 0; nt < 4; ++nt) { pa[nt] = *(const bf16x8*)(p_rd + nt * 16 * PRS); pb[nt] = *(const bf16x8*)(p_rd + nt * 16 * PRS + 64); }
;             RT_CB();
; #pragma unroll
;             for (int nt = 0; nt < 4; ++nt) { o[nt] = MFMA16(pa[nt], vf0, o[nt]); o[nt] = MFMA16(pb[nt], vf1, o[nt]); }
;         }
; #pragma unroll
;         for (int nt = 0; nt < 4; ++nt)
; #pragma unroll
;             for (int r = 0; r < 4; ++r) stg_w[(nt * 16 + r) * S2RS] = o[nt][r];
;         __syncthreads();
;         if (step + 1 < 68) R2_WRITE();
	v_mfma_f32_16x16x32_bf16 v[76:79], v[218:221], v[136:139], v[76:79]
	v_mul_f32_e32 v86, v158, v86
	v_mul_f32_e32 v87, v159, v87
	v_mul_f32_e32 v84, v160, v84
	v_mul_f32_e32 v85, v161, v85
	v_mul_f32_e32 v82, v158, v82
	v_mul_f32_e32 v83, v159, v83
	v_mul_f32_e32 v80, v160, v80
	v_mul_f32_e32 v81, v161, v81
	ds_read_b64_tr_b16 v[218:219], v168 offset:0x180
	ds_read_b64_tr_b16 v[220:221], v168 offset:0x1280
	v_mfma_f32_16x16x32_bf16 v[76:79], v[222:225], v[140:143], v[76:79]
	ds_read_b64_tr_b16 v[222:223], v168 offset:0x4580
	ds_read_b64_tr_b16 v[224:225], v168 offset:0x5680
	v_mfma_f32_16x16x32_bf16 v[72:75], v[226:229], v[136:139], v[72:75]
	ds_read_b64_tr_b16 v[226:227], v168 offset:0x1a0
	ds_read_b64_tr_b16 v[228:229], v168 offset:0x12a0
	v_mfma_f32_16x16x32_bf16 v[72:75], v[232:235], v[140:143], v[72:75]
	ds_read_b64_tr_b16 v[232:233], v168 offset:0x45a0
	ds_read_b64_tr_b16 v[234:235], v168 offset:0x56a0
	s_waitcnt lgkmcnt(8)
	v_mfma_f32_16x16x32_bf16 v[84:87], v[236:239], v[136:139], v[84:87]
	v_mul_f32_e32 v94, v158, v94
	v_mul_f32_e32 v95, v159, v95
	v_mul_f32_e32 v92, v160, v92
	v_mul_f32_e32 v93, v161, v93
	v_mul_f32_e32 v102, v158, v102
	v_mul_f32_e32 v103, v159, v103
	v_mul_f32_e32 v100, v160, v100
	v_mul_f32_e32 v101, v161, v101
	ds_read_b64_tr_b16 v[236:237], v168 offset:0x1c0
	ds_read_b64_tr_b16 v[238:239], v168 offset:0x12c0
	v_mfma_f32_16x16x32_bf16 v[84:87], v[240:243], v[140:143], v[84:87]
	ds_read_b64_tr_b16 v[240:241], v168 offset:0x45c0
	ds_read_b64_tr_b16 v[242:243], v168 offset:0x56c0
	v_mfma_f32_16x16x32_bf16 v[80:83], v[244:247], v[136:139], v[80:83]
	ds_read_b64_tr_b16 v[244:245], v168 offset:0x1e0
	ds_read_b64_tr_b16 v[246:247], v168 offset:0x12e0
	v_mfma_f32_16x16x32_bf16 v[80:83], v[248:251], v[140:143], v[80:83]
	ds_read_b64_tr_b16 v[248:249], v168 offset:0x45e0
	ds_read_b64_tr_b16 v[250:251], v168 offset:0x56e0
	s_waitcnt lgkmcnt(8)
	v_mfma_f32_16x16x32_bf16 v[92:95], v[218:221], v[136:139], v[92:95]
	v_mul_f32_e32 v98, v158, v98
	v_mul_f32_e32 v99, v159, v99
	v_mul_f32_e32 v96, v160, v96
	v_mul_f32_e32 v97, v161, v97
	v_mul_f32_e32 v90, v158, v90
	v_mul_f32_e32 v91, v159, v91
	v_mul_f32_e32 v88, v160, v88
	v_mul_f32_e32 v89, v161, v89
	s_waitcnt lgkmcnt(0)
	v_mfma_f32_16x16x32_bf16 v[100:103], v[226:229], v[136:139], v[100:103]
	v_mfma_f32_16x16x32_bf16 v[92:95], v[222:225], v[140:143], v[92:95]
	v_mfma_f32_16x16x32_bf16 v[100:103], v[232:235], v[140:143], v[100:103]
	v_mfma_f32_16x16x32_bf16 v[96:99], v[236:239], v[136:139], v[96:99]
	s_waitcnt lgkmcnt(0)
	s_barrier
	v_mfma_f32_16x16x32_bf16 v[88:91], v[244:247], v[136:139], v[88:91]
	v_mfma_f32_16x16x32_bf16 v[96:99], v[240:243], v[140:143], v[96:99]
	v_mfma_f32_16x16x32_bf16 v[88:91], v[248:251], v[140:143], v[88:91]
	ds_read_b128 v[136:139], v217
	ds_read_b128 v[140:143], v217 offset:64
	ds_read_b128 v[218:221], v217 offset:2304
	ds_read_b128 v[222:225], v217 offset:2368
	ds_read_b128 v[226:229], v217 offset:4608
	ds_read_b128 v[232:235], v217 offset:4672
	ds_read_b128 v[236:239], v217 offset:6912
	ds_read_b128 v[240:243], v217 offset:6976
	s_waitcnt lgkmcnt(7)
	v_mfma_f32_16x16x32_bf16 v[132:135], v[136:139], v[120:123], v[132:135]
	s_andn2_b64 vcc, exec, s[0:1]
	s_waitcnt lgkmcnt(5)
	v_mfma_f32_16x16x32_bf16 v[128:131], v[218:221], v[120:123], v[128:131]
	v_mfma_f32_16x16x32_bf16 v[132:135], v[140:143], v[124:127], v[132:135]
	s_waitcnt lgkmcnt(3)
	v_mfma_f32_16x16x32_bf16 v[116:119], v[226:229], v[120:123], v[116:119]
	v_mfma_f32_16x16x32_bf16 v[128:131], v[222:225], v[124:127], v[128:131]
	s_nop 4
	ds_write2_b32 v208, v132, v133 offset1:132
	v_add_u32_e32 v132, 0x400, v208
	ds_write2_b32 v132, v134, v135 offset0:8 offset1:140
	s_waitcnt lgkmcnt(3)
	v_mfma_f32_16x16x32_bf16 v[112:115], v[236:239], v[120:123], v[112:115]
	v_add_u32_e32 v132, 0x2000, v208
	ds_write2_b32 v132, v128, v129 offset0:64 offset1:196
	v_add_u32_e32 v128, 0x2400, v208
	v_mfma_f32_16x16x32_bf16 v[116:119], v[232:235], v[124:127], v[116:119]
	ds_write2_b32 v128, v130, v131 offset0:72 offset1:204
	v_add_u32_e32 v128, 0x4200, v208
	s_waitcnt lgkmcnt(4)
	v_mfma_f32_16x16x32_bf16 v[112:115], v[240:243], v[124:127], v[112:115]
	s_nop 3
	ds_write2_b32 v128, v116, v117 offset1:132
	v_add_u32_e32 v116, 0x4600, v208
	ds_write2_b32 v116, v118, v119 offset0:8 offset1:140
	v_add_u32_e32 v116, 0x6200, v208
	ds_write2_b32 v116, v112, v113 offset0:64 offset1:196
	v_add_u32_e32 v112, 0x6600, v208
	ds_write2_b32 v112, v114, v115 offset0:72 offset1:204
	s_waitcnt lgkmcnt(0)
	s_barrier
	ds_read_b128 v[112:115], v209
	ds_read_b128 v[120:123], v209 offset:16
	s_cbranch_vccnz .Lscan1_skipw
	s_waitcnt vmcnt(9)
	ds_write_b128 v200, v[0:3]
	s_waitcnt vmcnt(8)
	ds_write_b128 v201, v[4:7] offset:33792
	s_waitcnt vmcnt(7)
	ds_write_b128 v202, v[8:11]
	s_waitcnt vmcnt(6)
	ds_write_b128 v203, v[12:15] offset:33792
	s_waitcnt vmcnt(5)
	ds_write_b128 v204, v[16:19]
	s_waitcnt vmcnt(4)
	ds_write_b128 v205, v[20:23] offset:33792
	s_waitcnt vmcnt(3)
	ds_write_b128 v206, v[24:27]
	s_waitcnt vmcnt(2)
	ds_write_b128 v207, v[28:31] offset:33792
	s_waitcnt vmcnt(1)
	ds_write_b128 v210, v[32:35]
	s_waitcnt vmcnt(0)
	ds_write_b128 v211, v[36:39]
; DI float bflo(unsigned w) { return __uint_as_float(w << 16); }
; DI float bfhi(unsigned w) { return __uint_as_float(w & 0xffff0000u); }
; DI void store8(bf16_t* p, f32x4 a, f32x4 b) { u32x4 w = {cvt_pk_bf16(a[0], a[1]), cvt_pk_bf16(a[2], a[3]), cvt_pk_bf16(b[0], b[1]), cvt_pk_bf16(b[2], b[3])}; *(u32x4*)p = w; }
; template <int FWD, class BarrierFn>
; DI void scan2_dir(const bf16_t* __restrict__ Qg, const bf16_t* __restrict__ Kg, bf16_t* Vg, bf16_t* Tg, bf16_t* TCB, float* stats, int b, int h, int sl, float lg, char* lds, const BarrierFn& gbar) {
;     ...
;         {
;             bf16_t* dst = (fin ? Vg : ((!FWD && step < 4) ? TCB - (size_t)TL * 2048 : Tg));
; #pragma unroll
;             for (int hf = 0; hf < 2; ++hf) {
;                 const float* sr = stg_r + hf * 32 * S2RS; const float xi = hf ? xi1 : xi0;
;                 f32x4 b0 = *(const f32x4*)sr * xi, b1 = *(const f32x4*)(sr + 4) * xi;
;                 if (fin) { const bf16x8 tvv = hf ? tv1 : tv0; const u32x4 ow = *reinterpret_cast<const u32x4*>(&tvv);
;                     b0[0] += bflo(ow[0]); b0[1] += bfhi(ow[0]); b0[2] += bflo(ow[1]); b0[3] += bfhi(ow[1]); b1[0] += bflo(ow[2]); b1[1] += bfhi(ow[2]); b1[2] += bflo(ow[3]); b1[3] += bfhi(ow[3]); }
;                 const size_t row = (size_t)(rb + srow + 32 * hf);
;                 store8(dst + row * 2048 + vcol + scp * 8, b0, b1);
;                 if (fin) {
;                     float sm = (b0[0] + b0[1]) + (b0[2] + b0[3]) + (b1[0] + b1[1]) + (b1[2] + b1[3]);
;                     float sq = (b0[0] * b0[0] + b0[1] * b0[1]) + (b0[2] * b0[2] + b0[3] * b0[3]) + (b1[0] * b1[0] + b1[1] * b1[1]) + (b1[2] * b1[2] + b1[3] * b1[3]);
; #pragma unroll
;                     for (int o_ = 1; o_ < 16; o_ <<= 1) { sm += __shfl_xor(sm, o_, 64); sq += __shfl_xor(sq, o_, 64); }
;                     if (scp == 0) { float* sp = stats + (row * 4 + h) * 2; unsafeAtomicAdd(sp, sm); unsafeAtomicAdd(sp + 1, sq); }
;                 }
.LBB0_364:
	s_andn2_b64 vcc, exec, s[72:73]
	s_waitcnt lgkmcnt(11)
	v_pk_mul_f32 v[116:117], v[162:163], v[114:115]
	s_waitcnt lgkmcnt(10)
	v_pk_mul_f32 v[114:115], v[152:153], v[120:121]
	v_cndmask_b32_e64 v120, 0, 1, s[72:73]
	v_pk_mul_f32 v[118:119], v[152:153], v[112:113]
	v_pk_mul_f32 v[112:113], v[162:163], v[122:123]
	v_cmp_ne_u32_e64 s[0:1], 1, v120
	s_cbranch_vccnz .LBB0_366
	s_waitcnt vmcnt(1)
	v_lshlrev_b32_e32 v120, 16, v108
	v_and_b32_e32 v121, 0xffff0000, v108
	v_lshlrev_b32_e32 v108, 16, v109
	v_and_b32_e32 v109, 0xffff0000, v109
	v_pk_add_f32 v[116:117], v[116:117], v[108:109]
	v_lshlrev_b32_e32 v108, 16, v110
	v_and_b32_e32 v109, 0xffff0000, v110
	v_pk_add_f32 v[114:115], v[114:115], v[108:109]
	v_lshlrev_b32_e32 v108, 16, v111
	v_and_b32_e32 v109, 0xffff0000, v111
	v_pk_add_f32 v[118:119], v[118:119], v[120:121]
	v_pk_add_f32 v[112:113], v[112:113], v[108:109]
.LBB0_366:
	s_and_b64 s[46:47], s[72:73], exec
	s_cselect_b32 s47, s97, s59
	s_cselect_b32 s46, s96, s58
	s_lshl_b32 s71, s63, 1
	s_add_u32 s46, s46, s71
	s_addc_u32 s47, s47, 0
	v_lshlrev_b32_e32 v180, 1, v154
	s_waitcnt vmcnt(1)
	v_lshl_add_u64 v[108:109], s[46:47], 0, v[180:181]
	v_lshlrev_b64 v[110:111], 12, v[166:167]
	v_lshl_add_u64 v[110:111], v[108:109], 0, v[110:111]
	s_and_b64 vcc, exec, s[0:1]
	v_cvt_pk_bf16_f32 v120, v118, v119
	v_cvt_pk_bf16_f32 v121, v116, v117
	v_cvt_pk_bf16_f32 v122, v114, v115
	v_cvt_pk_bf16_f32 v123, v112, v113
	global_store_dwordx4 v[110:111], v[120:123], off
	s_cbranch_vccnz .LBB0_370
	v_add_f32_e32 v110, v118, v119
	v_add_f32_e32 v111, v116, v117
	v_add_f32_e32 v110, v110, v111
	v_add_f32_e32 v111, v114, v115
	v_add_f32_e32 v110, v110, v111
	v_add_f32_e32 v111, v112, v113
	v_add_f32_e32 v110, v111, v110
	v_mul_f32_e32 v111, v119, v119
	v_mul_f32_e32 v117, v117, v117
	v_fmac_f32_e32 v111, v118, v118
	v_fmac_f32_e32 v117, v116, v116
	v_mul_f32_e32 v115, v115, v115
	v_add_f32_e32 v111, v111, v117
	v_fmac_f32_e32 v115, v114, v114
	v_mul_f32_e32 v113, v113, v113
	v_add_f32_e32 v111, v111, v115
	v_fmac_f32_e32 v113, v112, v112
	v_add_f32_e32 v111, v113, v111
	s_nop 1
	v_add_f32_dpp v110, v110, v110 quad_perm:[1,0,3,2] row_mask:0xf bank_mask:0xf
	v_add_f32_dpp v111, v111, v111 quad_perm:[1,0,3,2] row_mask:0xf bank_mask:0xf
	s_nop 1
	v_add_f32_dpp v110, v110, v110 quad_perm:[2,3,0,1] row_mask:0xf bank_mask:0xf
	v_add_f32_dpp v111, v111, v111 quad_perm:[2,3,0,1] row_mask:0xf bank_mask:0xf
	s_nop 1
	v_add_f32_dpp v110, v110, v110 row_half_mirror row_mask:0xf bank_mask:0xf
	v_add_f32_dpp v111, v111, v111 row_half_mirror row_mask:0xf bank_mask:0xf
	s_nop 1
	v_add_f32_dpp v112, v110, v110 row_mirror row_mask:0xf bank_mask:0xf
	v_add_f32_dpp v113, v111, v111 row_mirror row_mask:0xf bank_mask:0xf
	s_and_saveexec_b64 s[46:47], s[4:5]
	s_cbranch_execz .LBB0_369
	v_readlane_b32 s72, v254, 23
	v_lshlrev_b64 v[110:111], 5, v[166:167]
	v_readlane_b32 s73, v254, 24
	s_nop 1
	v_lshl_add_u64 v[110:111], s[72:73], 0, v[110:111]
	global_atomic_add_f32 v[110:111], v112, off
	global_atomic_add_f32 v[110:111], v113, off offset:4

; template <int FWD, class BarrierFn>
; DI void scan2_dir(const bf16_t* __restrict__ Qg, const bf16_t* __restrict__ Kg, bf16_t* Vg, bf16_t* Tg, bf16_t* TCB, float* stats, int b, int h, int sl, float lg, char* lds, const BarrierFn& gbar) {
;     ...
;         if (step + 1 < 68) R2_WRITE();
.Lscan1_skipw:
	s_waitcnt lgkmcnt(0)
	s_branch .LBB0_364

; DI unsigned cvt_pk_bf16(float lo, float hi) { unsigned r; asm volatile("v_cvt_pk_bf16_f32 %0, %1, %2" : "=v"(r) : "v"(lo), "v"(hi)); return r; }
; #define RT_LGKM(n) do { asm volatile("s_waitcnt lgkmcnt(" #n ")" ::: "memory"); __builtin_amdgcn_sched_barrier(0); } while (0)
; template <int FWD, class BarrierFn>
; DI void scan2_dir(const bf16_t* __restrict__ Qg, const bf16_t* __restrict__ Kg, bf16_t* Vg, bf16_t* Tg, bf16_t* TCB, float* stats, int b, int h, int sl, float lg, char* lds, const BarrierFn& gbar) {
;     ...
;         {
;             f32x4 s0 = {0.f, 0.f, 0.f, 0.f}, s1 = {0.f, 0.f, 0.f, 0.f};
;             bf16x8 ak[2], aq0[2], aq1[2], bk[2], bq0[2], bq1[2];
;     ...
;             ST_LOAD(ak, aq0, aq1, 0); ST_LOAD(bk, bq0, bq1, 2);
;             ST_MMA(ak, aq0, aq1); ST_LOAD(ak, aq0, aq1, 4);
;             ST_MMA(bk, bq0, bq1); ST_LOAD(bk, bq0, bq1, 6);
;             ST_MMA(ak, aq0, aq1); ST_MMA(bk, bq0, bq1);
;     ...
;             const int n0 = 16 * qt0 + c, n1 = n0 + 16, mb = 16 * kt + 4 * g;
;             float p0[4], p1[4];
; #pragma unroll
;             for (int jj = 0; jj < 4; ++jj) { const int m = mb + jj; const float wmv = wm[jj];
;                 const bool k0 = FWD ? (m <= n0) : (m > n0), k1 = FWD ? (m <= n1) : (m > n1);
;                 p0[jj] = k0 ? s0[jj] * wmv : 0.f; p1[jj] = k1 ? s1[jj] * wmv : 0.f; }
;             u32x2 w0 = {cvt_pk_bf16(p0[0], p0[1]), cvt_pk_bf16(p0[2], p0[3])}, w1 = {cvt_pk_bf16(p1[0], p1[1]), cvt_pk_bf16(p1[2], p1[3])};
;             *(u32x2*)(lds + P2_OFF + n0 * PRS + mb * 2) = w0; *(u32x2*)(lds + P2_OFF + n1 * PRS + mb * 2) = w1;
;         }
;         f32x4 o[4];
; #pragma unroll
;         for (int nt = 0; nt < 4; ++nt) o[nt] = (f32x4){0.f, 0.f, 0.f, 0.f};
;         {
;             bf16x8 qa[4], qb[4];
;     ...
;             qs_load<0>(qa, qs_b); qs_load<1>(qb, qs_b);
;             RT_LGKM(8); QS_MMA(qa, 0); qs_load<2>(qa, qs_b);
;             RT_LGKM(8); QS_MMA(qb, 1); qs_load<3>(qb, qs_b);
;             RT_LGKM(8); QS_MMA(qa, 2); qs_load<4>(qa, qs_b);
;             RT_LGKM(8); QS_MMA(qb, 3); qs_load<5>(qb, qs_b);
;             RT_LGKM(8); QS_MMA(qa, 4); qs_load<6>(qa, qs_b);
;             RT_LGKM(8); QS_MMA(qb, 5); qs_load<7>(qb, qs_b);
;             RT_LGKM(8); QS_MMA(qa, 6);
;             RT_LGKM(0); QS_MMA(qb, 7);
.LBB0_443:
	ds_read_b128 v[112:115], v212 offset:33792
	ds_read_b128 v[116:119], v212 offset:33856
	ds_read_b128 v[120:123], v213
	ds_read_b128 v[124:127], v213 offset:64
	ds_read_b128 v[128:131], v213 offset:8448
	ds_read_b128 v[132:135], v213 offset:8512
	ds_read_b128 v[136:139], v212 offset:33920
	ds_read_b128 v[140:143], v212 offset:33984
	ds_read_b128 v[216:219], v213 offset:128
	ds_read_b128 v[220:223], v213 offset:192
	ds_read_b128 v[224:227], v213 offset:8576
	ds_read_b128 v[232:235], v213 offset:8640
	s_waitcnt lgkmcnt(9)
	v_mfma_f32_16x16x32_bf16 v[120:123], v[112:115], v[120:123], 0
	s_waitcnt lgkmcnt(7)
	v_mfma_f32_16x16x32_bf16 v[112:115], v[112:115], v[128:131], 0
	ds_read_b128 v[128:131], v212 offset:34048
	ds_read_b128 v[236:239], v212 offset:34112
	ds_read_b128 v[240:243], v213 offset:256
	ds_read_b128 v[244:247], v213 offset:320
	v_mfma_f32_16x16x32_bf16 v[120:123], v[116:119], v[124:127], v[120:123]
	ds_read_b128 v[124:127], v213 offset:8704
	ds_read_b128 v[248:251], v213 offset:8768
	s_waitcnt lgkmcnt(12)
	v_mfma_f32_16x16x32_bf16 v[112:115], v[116:119], v[132:135], v[112:115]
	s_waitcnt lgkmcnt(9)
	v_mfma_f32_16x16x32_bf16 v[116:119], v[136:139], v[216:219], v[120:123]
	s_waitcnt lgkmcnt(7)
	v_mfma_f32_16x16x32_bf16 v[112:115], v[136:139], v[224:227], v[112:115]
	s_nop 0
	ds_read_b128 v[120:123], v212 offset:34176
	ds_read_b128 v[132:135], v212 offset:34240
	ds_read_b128 v[136:139], v213 offset:384
	ds_read_b128 v[216:219], v213 offset:448
	v_mfma_f32_16x16x32_bf16 v[116:119], v[140:143], v[220:223], v[116:119]
	ds_read_b128 v[220:223], v213 offset:8832
	ds_read_b128 v[224:227], v213 offset:8896
	s_waitcnt lgkmcnt(12)
	v_mfma_f32_16x16x32_bf16 v[112:115], v[140:143], v[232:235], v[112:115]
	s_waitcnt lgkmcnt(9)
	v_mfma_f32_16x16x32_bf16 v[116:119], v[128:131], v[240:243], v[116:119]
	s_waitcnt lgkmcnt(7)
	v_mfma_f32_16x16x32_bf16 v[112:115], v[128:131], v[124:127], v[112:115]
	v_mfma_f32_16x16x32_bf16 v[116:119], v[236:239], v[244:247], v[116:119]
	s_waitcnt lgkmcnt(6)
	v_mfma_f32_16x16x32_bf16 v[112:115], v[236:239], v[248:251], v[112:115]
	s_waitcnt lgkmcnt(3)
	v_mfma_f32_16x16x32_bf16 v[116:119], v[120:123], v[136:139], v[116:119]
	s_waitcnt lgkmcnt(1)
	v_mfma_f32_16x16x32_bf16 v[112:115], v[120:123], v[220:223], v[112:115]
	v_mfma_f32_16x16x32_bf16 v[116:119], v[132:135], v[216:219], v[116:119]
	s_waitcnt lgkmcnt(0)
	v_mfma_f32_16x16x32_bf16 v[112:115], v[132:135], v[224:227], v[112:115]
	s_nop 7
	v_mul_f32_e32 v112, v167, v112
	v_mul_f32_e32 v113, v168, v113
	v_mul_f32_e32 v116, v167, v116
	v_cndmask_b32_e64 v120, 0, v112, s[8:9]
	v_mul_f32_e32 v112, v168, v117
	v_cndmask_b32_e64 v117, v113, 0, s[12:13]
	v_mul_f32_e32 v113, v169, v118
	v_mul_f32_e32 v114, v169, v114
	v_cndmask_b32_e64 v116, 0, v116, s[6:7]
	v_cndmask_b32_e64 v112, v112, 0, s[10:11]
	v_cndmask_b32_e64 v113, 0, v113, s[14:15]
	v_cndmask_b32_e64 v118, 0, v114, s[16:17]
	v_mul_f32_e32 v114, v170, v119
	v_mul_f32_e32 v115, v170, v115
	v_cndmask_b32_e64 v114, 0, v114, s[18:19]
	v_cndmask_b32_e64 v115, 0, v115, s[20:21]
	v_cvt_pk_bf16_f32 v112, v116, v112
	v_cvt_pk_bf16_f32 v113, v113, v114
	v_add_u32_e32 v116, v210, v211
	v_cvt_pk_bf16_f32 v114, v120, v117
	v_cvt_pk_bf16_f32 v115, v118, v115
	ds_write_b64 v116, v[112:113]
	ds_write_b64 v214, v[114:115]
	ds_read_b64 v[112:113], v197 offset:0
	ds_read_b64 v[114:115], v197 offset:32
	ds_read_b64 v[116:117], v197 offset:0x2100
	ds_read_b64 v[118:119], v197 offset:0x2120
	ds_read_b64 v[120:121], v197 offset:0x4200
	ds_read_b64 v[122:123], v197 offset:0x4220
	ds_read_b64 v[124:125], v197 offset:0x6300
	ds_read_b64 v[126:127], v197 offset:0x6320
	ds_read_b64 v[128:129], v197 offset:64
	ds_read_b64 v[130:131], v197 offset:0x60
	ds_read_b64 v[132:133], v197 offset:0x2140
	ds_read_b64 v[134:135], v197 offset:0x2160
	ds_read_b64 v[136:137], v197 offset:0x4240
	ds_read_b64 v[138:139], v197 offset:0x4260
	ds_read_b64 v[140:141], v197 offset:0x6340
	ds_read_b64 v[142:143], v197 offset:0x6360
	s_waitcnt lgkmcnt(8)
	v_cvt_pk_bf16_f32 v216, v40, v41
	v_cvt_pk_bf16_f32 v217, v42, v43
	v_cvt_pk_bf16_f32 v218, v44, v45
	v_cvt_pk_bf16_f32 v219, v46, v47
	s_nop 0
	v_mfma_f32_16x16x32_bf16 v[112:115], v[112:115], v[216:219], 0
	v_mfma_f32_16x16x32_bf16 v[116:119], v[116:119], v[216:219], 0
	v_mfma_f32_16x16x32_bf16 v[120:123], v[120:123], v[216:219], 0
	v_mfma_f32_16x16x32_bf16 v[124:127], v[124:127], v[216:219], 0
	ds_read_b64 v[216:217], v197 offset:0x80
	ds_read_b64 v[218:219], v197 offset:0xa0
	ds_read_b64 v[220:221], v197 offset:0x2180
	ds_read_b64 v[222:223], v197 offset:0x21a0
	ds_read_b64 v[224:225], v197 offset:0x4280
	ds_read_b64 v[226:227], v197 offset:0x42a0
	ds_read_b64 v[232:233], v197 offset:0x6380
	ds_read_b64 v[234:235], v197 offset:0x63a0
	s_waitcnt lgkmcnt(8)
	v_cvt_pk_bf16_f32 v236, v52, v53
	v_cvt_pk_bf16_f32 v237, v54, v55
	v_cvt_pk_bf16_f32 v238, v48, v49
	v_cvt_pk_bf16_f32 v239, v50, v51
	s_nop 0
	v_mfma_f32_16x16x32_bf16 v[112:115], v[128:131], v[236:239], v[112:115]
	ds_read_b64 v[128:129], v197 offset:0xc0
	ds_read_b64 v[130:131], v197 offset:0xe0
	v_mfma_f32_16x16x32_bf16 v[116:119], v[132:135], v[236:239], v[116:119]
	ds_read_b64 v[132:133], v197 offset:0x21c0
	ds_read_b64 v[134:135], v197 offset:0x21e0
	v_mfma_f32_16x16x32_bf16 v[120:123], v[136:139], v[236:239], v[120:123]
	ds_read_b64 v[136:137], v197 offset:0x42c0
	ds_read_b64 v[138:139], v197 offset:0x42e0
	v_mfma_f32_16x16x32_bf16 v[124:127], v[140:143], v[236:239], v[124:127]
	ds_read_b64 v[140:141], v197 offset:0x63c0
	ds_read_b64 v[142:143], v197 offset:0x63e0
	s_waitcnt lgkmcnt(8)
; template <int OFF> DI s16x4 tr_rd(unsigned addr) { s16x4 r; asm volatile("ds_read_b64_tr_b16 %0, %1 offset:%2" : "=&v"(r) : "v"(addr), "i"(OFF) : "memory"); return r; }
; DI bf16x8 cat(s16x4 l, s16x4 h) { return (bf16x8){l[0], l[1], l[2], l[3], h[0], h[1], h[2], h[3]}; }
; #define RT_LGKM(n) do { asm volatile("s_waitcnt lgkmcnt(" #n ")" ::: "memory"); __builtin_amdgcn_sched_barrier(0); } while (0)
; template <int FWD, class BarrierFn>
; DI void scan2_dir(const bf16_t* __restrict__ Qg, const bf16_t* __restrict__ Kg, bf16_t* Vg, bf16_t* Tg, bf16_t* TCB, float* stats, int b, int h, int sl, float lg, char* lds, const BarrierFn& gbar) {
;     ...
;             qs_load<0>(qa, qs_b); qs_load<1>(qb, qs_b);
;             RT_LGKM(8); QS_MMA(qa, 0); qs_load<2>(qa, qs_b);
;             RT_LGKM(8); QS_MMA(qb, 1); qs_load<3>(qb, qs_b);
;             RT_LGKM(8); QS_MMA(qa, 2); qs_load<4>(qa, qs_b);
;             RT_LGKM(8); QS_MMA(qb, 3); qs_load<5>(qb, qs_b);
;             RT_LGKM(8); QS_MMA(qa, 4); qs_load<6>(qa, qs_b);
;             RT_LGKM(8); QS_MMA(qb, 5); qs_load<7>(qb, qs_b);
;             RT_LGKM(8); QS_MMA(qa, 6);
;             RT_LGKM(0); QS_MMA(qb, 7);
;     ...
;         }
;         bf16x8 vf0, vf1;
;         {
;             const s16x4 l0 = tr_rd<0>(vb_tr), h0 = tr_rd<8 * V2RS>(vb_tr), l1 = tr_rd<32 * V2RS>(vb_tr), h1 = tr_rd<40 * V2RS>(vb_tr);
;             KT8 ka, kb2;
;             kt_load<0>(ka, kb_tr);
;             RT_LGKM(8);
;             vf0 = cat(l0, h0); vf1 = cat(l1, h1);
	v_cvt_pk_bf16_f32 v236, v60, v61
	v_cvt_pk_bf16_f32 v237, v62, v63
	v_cvt_pk_bf16_f32 v238, v56, v57
	v_cvt_pk_bf16_f32 v239, v58, v59
	s_nop 0
	v_mfma_f32_16x16x32_bf16 v[112:115], v[216:219], v[236:239], v[112:115]
	ds_read_b64 v[216:217], v197 offset:0x100
	ds_read_b64 v[218:219], v197 offset:0x120
	v_mfma_f32_16x16x32_bf16 v[116:119], v[220:223], v[236:239], v[116:119]
	ds_read_b64 v[220:221], v197 offset:0x2200
	ds_read_b64 v[222:223], v197 offset:0x2220
	v_mfma_f32_16x16x32_bf16 v[120:123], v[224:227], v[236:239], v[120:123]
	ds_read_b64 v[224:225], v197 offset:0x4300
	ds_read_b64 v[226:227], v197 offset:0x4320
	v_mfma_f32_16x16x32_bf16 v[124:127], v[232:235], v[236:239], v[124:127]
	ds_read_b64 v[232:233], v197 offset:0x6400
	ds_read_b64 v[234:235], v197 offset:0x6420
	s_waitcnt lgkmcnt(8)
	v_cvt_pk_bf16_f32 v236, v68, v69
	v_cvt_pk_bf16_f32 v237, v70, v71
	v_cvt_pk_bf16_f32 v238, v64, v65
	v_cvt_pk_bf16_f32 v239, v66, v67
	s_nop 0
	v_mfma_f32_16x16x32_bf16 v[112:115], v[128:131], v[236:239], v[112:115]
	ds_read_b64 v[128:129], v197 offset:0x140
	ds_read_b64 v[130:131], v197 offset:0x160
	v_mfma_f32_16x16x32_bf16 v[116:119], v[132:135], v[236:239], v[116:119]
	ds_read_b64 v[132:133], v197 offset:0x2240
	ds_read_b64 v[134:135], v197 offset:0x2260
	v_mfma_f32_16x16x32_bf16 v[120:123], v[136:139], v[236:239], v[120:123]
	ds_read_b64 v[136:137], v197 offset:0x4340
	ds_read_b64 v[138:139], v197 offset:0x4360
	v_mfma_f32_16x16x32_bf16 v[124:127], v[140:143], v[236:239], v[124:127]
	ds_read_b64 v[140:141], v197 offset:0x6440
	ds_read_b64 v[142:143], v197 offset:0x6460
	s_waitcnt lgkmcnt(8)
	v_cvt_pk_bf16_f32 v236, v76, v77
	v_cvt_pk_bf16_f32 v237, v78, v79
	v_cvt_pk_bf16_f32 v238, v72, v73
	v_cvt_pk_bf16_f32 v239, v74, v75
	s_nop 0
	v_mfma_f32_16x16x32_bf16 v[112:115], v[216:219], v[236:239], v[112:115]
	ds_read_b64 v[216:217], v197 offset:0x180
	ds_read_b64 v[218:219], v197 offset:0x1a0
	v_mfma_f32_16x16x32_bf16 v[116:119], v[220:223], v[236:239], v[116:119]
	ds_read_b64 v[220:221], v197 offset:0x2280
	ds_read_b64 v[222:223], v197 offset:0x22a0
	v_mfma_f32_16x16x32_bf16 v[120:123], v[224:227], v[236:239], v[120:123]
	ds_read_b64 v[224:225], v197 offset:0x4380
	ds_read_b64 v[226:227], v197 offset:0x43a0
	v_mfma_f32_16x16x32_bf16 v[124:127], v[232:235], v[236:239], v[124:127]
	ds_read_b64 v[232:233], v197 offset:0x6480
	ds_read_b64 v[234:235], v197 offset:0x64a0
	s_waitcnt lgkmcnt(8)
	v_cvt_pk_bf16_f32 v236, v84, v85
	v_cvt_pk_bf16_f32 v237, v86, v87
	v_cvt_pk_bf16_f32 v238, v80, v81
	v_cvt_pk_bf16_f32 v239, v82, v83
	s_nop 0
	v_mfma_f32_16x16x32_bf16 v[112:115], v[128:131], v[236:239], v[112:115]
	ds_read_b64 v[128:129], v197 offset:0x1c0
	ds_read_b64 v[130:131], v197 offset:0x1e0
	v_mfma_f32_16x16x32_bf16 v[120:123], v[136:139], v[236:239], v[120:123]
	ds_read_b64 v[136:137], v197 offset:0x22c0
	ds_read_b64 v[138:139], v197 offset:0x22e0
	v_mfma_f32_16x16x32_bf16 v[124:127], v[140:143], v[236:239], v[124:127]
	ds_read_b64 v[140:141], v197 offset:0x43c0
	ds_read_b64 v[142:143], v197 offset:0x43e0
	v_mfma_f32_16x16x32_bf16 v[116:119], v[132:135], v[236:239], v[116:119]
	ds_read_b64 v[236:237], v197 offset:0x64c0
	ds_read_b64 v[238:239], v197 offset:0x64e0
	s_waitcnt lgkmcnt(8)
	v_cvt_pk_bf16_f32 v132, v92, v93
	v_cvt_pk_bf16_f32 v133, v94, v95
	v_cvt_pk_bf16_f32 v134, v100, v101
	v_cvt_pk_bf16_f32 v135, v102, v103
	s_waitcnt lgkmcnt(0)
	s_nop 0
	v_mfma_f32_16x16x32_bf16 v[112:115], v[216:219], v[132:135], v[112:115]
	v_mfma_f32_16x16x32_bf16 v[116:119], v[220:223], v[132:135], v[116:119]
	v_mfma_f32_16x16x32_bf16 v[120:123], v[224:227], v[132:135], v[120:123]
	v_mfma_f32_16x16x32_bf16 v[124:127], v[232:235], v[132:135], v[124:127]
	v_cvt_pk_bf16_f32 v216, v96, v97
	v_cvt_pk_bf16_f32 v217, v98, v99
	v_cvt_pk_bf16_f32 v218, v88, v89
	v_cvt_pk_bf16_f32 v219, v90, v91
	s_nop 0
	v_mfma_f32_16x16x32_bf16 v[132:135], v[128:131], v[216:219], v[112:115]
	v_mfma_f32_16x16x32_bf16 v[128:131], v[136:139], v[216:219], v[116:119]
	v_mfma_f32_16x16x32_bf16 v[116:119], v[140:143], v[216:219], v[120:123]
	ds_read_b64_tr_b16 v[120:121], v196 offset:0
	ds_read_b64_tr_b16 v[122:123], v196 offset:0x900
	v_mfma_f32_16x16x32_bf16 v[112:115], v[236:239], v[216:219], v[124:127]
	ds_read_b64_tr_b16 v[124:125], v196 offset:0x2400
	ds_read_b64_tr_b16 v[126:127], v196 offset:0x2d00
	ds_read_b64_tr_b16 v[216:217], v166 offset:0
	ds_read_b64_tr_b16 v[218:219], v166 offset:0x1100
	ds_read_b64_tr_b16 v[220:221], v166 offset:0x4400
	ds_read_b64_tr_b16 v[222:223], v166 offset:0x5500
	ds_read_b64_tr_b16 v[224:225], v166 offset:32
	ds_read_b64_tr_b16 v[226:227], v166 offset:0x1120
	ds_read_b64_tr_b16 v[232:233], v166 offset:0x4420
	ds_read_b64_tr_b16 v[234:235], v166 offset:0x5520
	s_waitcnt lgkmcnt(8)
; DI unsigned cvt_pk_bf16(float lo, float hi) { unsigned r; asm volatile("v_cvt_pk_bf16_f32 %0, %1, %2" : "=v"(r) : "v"(lo), "v"(hi)); return r; }
; DI float bf2f(bf16_t b) { return __uint_as_float(((unsigned)b) << 16); }
; DI bf16x8 cat(s16x4 l, s16x4 h) { return (bf16x8){l[0], l[1], l[2], l[3], h[0], h[1], h[2], h[3]}; }
; #define RT_LGKM(n) do { asm volatile("s_waitcnt lgkmcnt(" #n ")" ::: "memory"); __builtin_amdgcn_sched_barrier(0); } while (0)
; template <int FWD, class BarrierFn>
; DI void scan2_dir(const bf16_t* __restrict__ Qg, const bf16_t* __restrict__ Kg, bf16_t* Vg, bf16_t* Tg, bf16_t* TCB, float* stats, int b, int h, int sl, float lg, char* lds, const BarrierFn& gbar) {
;     ...
;             vf0 = cat(l0, h0); vf1 = cat(l1, h1);
;             bf16x8 vz0, vz1;
;             {
;                 float f[8];
; #pragma unroll
;                 for (int jj = 0; jj < 8; ++jj) f[jj] = bf2f((bf16_t)vf0[jj]) * zt0[jj];
;                 u32x4 w = {cvt_pk_bf16(f[0], f[1]), cvt_pk_bf16(f[2], f[3]), cvt_pk_bf16(f[4], f[5]), cvt_pk_bf16(f[6], f[7])};
;                 vz0 = *reinterpret_cast<bf16x8*>(&w);
; #pragma unroll
;                 for (int jj = 0; jj < 8; ++jj) f[jj] = bf2f((bf16_t)vf1[jj]) * zt1[jj];
;                 u32x4 w2 = {cvt_pk_bf16(f[0], f[1]), cvt_pk_bf16(f[2], f[3]), cvt_pk_bf16(f[4], f[5]), cvt_pk_bf16(f[6], f[7])};
;                 vz1 = *reinterpret_cast<bf16x8*>(&w2);
;             }
; #pragma unroll
;             for (int t = 0; t < 16; ++t) st[t] = st[t] * gC;
;             kt_load<2>(kb2, kb_tr);  RT_LGKM(8); kt_mma(st[0], st[1], ka, vz0, vz1);
;             kt_load<4>(ka, kb_tr);   RT_LGKM(8); kt_mma(st[2], st[3], kb2, vz0, vz1);
;             kt_load<6>(kb2, kb_tr);  RT_LGKM(8); kt_mma(st[4], st[5], ka, vz0, vz1);
;             kt_load<8>(ka, kb_tr);   RT_LGKM(8); kt_mma(st[6], st[7], kb2, vz0, vz1);
;             kt_load<10>(kb2, kb_tr); RT_LGKM(8); kt_mma(st[8], st[9], ka, vz0, vz1);
;             kt_load<12>(ka, kb_tr);  RT_LGKM(8); kt_mma(st[10], st[11], kb2, vz0, vz1);
;             kt_load<14>(kb2, kb_tr); RT_LGKM(8); kt_mma(st[12], st[13], ka, vz0, vz1);
	s_nop 1
	v_lshlrev_b32_e32 v136, 16, v120
	v_and_b32_e32 v137, 0xffff0000, v120
	v_lshlrev_b32_e32 v138, 16, v121
	v_and_b32_e32 v139, 0xffff0000, v121
	v_lshlrev_b32_e32 v140, 16, v122
	v_and_b32_e32 v141, 0xffff0000, v122
	v_lshlrev_b32_e32 v142, 16, v123
	v_and_b32_e32 v143, 0xffff0000, v123
	v_mul_f32_e32 v136, v171, v136
	v_mul_f32_e32 v137, v173, v137
	v_mul_f32_e32 v138, v175, v138
	v_mul_f32_e32 v139, v177, v139
	v_mul_f32_e32 v140, v179, v140
	v_mul_f32_e32 v141, v185, v141
	v_mul_f32_e32 v142, v187, v142
	v_mul_f32_e32 v143, v189, v143
	v_cvt_pk_bf16_f32 v136, v136, v137
	v_cvt_pk_bf16_f32 v137, v138, v139
	v_cvt_pk_bf16_f32 v138, v140, v141
	v_cvt_pk_bf16_f32 v139, v142, v143
	v_lshlrev_b32_e32 v140, 16, v124
	v_and_b32_e32 v141, 0xffff0000, v124
	v_lshlrev_b32_e32 v142, 16, v125
	v_and_b32_e32 v143, 0xffff0000, v125
	v_mul_f32_e32 v140, v172, v140
	v_mul_f32_e32 v141, v174, v141
	v_mul_f32_e32 v142, v176, v142
	v_mul_f32_e32 v143, v178, v143
	v_lshlrev_b32_e32 v153, 16, v126
	v_and_b32_e32 v228, 0xffff0000, v126
	v_lshlrev_b32_e32 v229, 16, v127
	v_and_b32_e32 v231, 0xffff0000, v127
	v_mul_f32_e32 v153, v184, v153
	v_mul_f32_e32 v228, v186, v228
	v_mul_f32_e32 v229, v188, v229
	v_mul_f32_e32 v231, v195, v231
	v_cvt_pk_bf16_f32 v140, v140, v141
	v_cvt_pk_bf16_f32 v141, v142, v143
	v_cvt_pk_bf16_f32 v142, v153, v228
	v_cvt_pk_bf16_f32 v143, v229, v231
	ds_read_b64_tr_b16 v[236:237], v166 offset:64
	ds_read_b64_tr_b16 v[238:239], v166 offset:0x1140
	ds_read_b64_tr_b16 v[240:241], v166 offset:0x4440
	ds_read_b64_tr_b16 v[242:243], v166 offset:0x5540
	ds_read_b64_tr_b16 v[244:245], v166 offset:0x60
	ds_read_b64_tr_b16 v[246:247], v166 offset:0x1160
	ds_read_b64_tr_b16 v[248:249], v166 offset:0x4460
	ds_read_b64_tr_b16 v[250:251], v166 offset:0x5560
	s_waitcnt lgkmcnt(8)
	v_mov_b32_e32 v153, v152
	v_mul_f32_e32 v42, v152, v42
	v_mul_f32_e32 v43, v153, v43
	v_mul_f32_e32 v40, v158, v40
	v_mul_f32_e32 v41, v159, v41
	v_mul_f32_e32 v46, v152, v46
	v_mul_f32_e32 v47, v153, v47
	v_mul_f32_e32 v44, v158, v44
	v_mul_f32_e32 v45, v159, v45
	v_mfma_f32_16x16x32_bf16 v[40:43], v[216:219], v[136:139], v[40:43]
	v_mul_f32_e32 v54, v152, v54
	v_mul_f32_e32 v55, v153, v55
	v_mul_f32_e32 v52, v158, v52
	v_mul_f32_e32 v53, v159, v53
	v_mul_f32_e32 v50, v152, v50
	v_mul_f32_e32 v51, v153, v51
	v_mul_f32_e32 v48, v158, v48
	v_mul_f32_e32 v49, v159, v49
	ds_read_b64_tr_b16 v[216:217], v166 offset:0x80
	ds_read_b64_tr_b16 v[218:219], v166 offset:0x1180
	v_mfma_f32_16x16x32_bf16 v[40:43], v[220:223], v[140:143], v[40:43]
	ds_read_b64_tr_b16 v[220:221], v166 offset:0x4480
	ds_read_b64_tr_b16 v[222:223], v166 offset:0x5580
	v_mfma_f32_16x16x32_bf16 v[44:47], v[224:227], v[136:139], v[44:47]
	ds_read_b64_tr_b16 v[224:225], v166 offset:0xa0
	ds_read_b64_tr_b16 v[226:227], v166 offset:0x11a0
	v_mfma_f32_16x16x32_bf16 v[44:47], v[232:235], v[140:143], v[44:47]
	ds_read_b64_tr_b16 v[232:233], v166 offset:0x44a0
	ds_read_b64_tr_b16 v[234:235], v166 offset:0x55a0
	s_waitcnt lgkmcnt(8)
	v_mfma_f32_16x16x32_bf16 v[52:55], v[236:239], v[136:139], v[52:55]
	v_mul_f32_e32 v62, v152, v62
	v_mul_f32_e32 v63, v153, v63
	v_mul_f32_e32 v60, v158, v60
	v_mul_f32_e32 v61, v159, v61
	v_mul_f32_e32 v58, v152, v58
	v_mul_f32_e32 v59, v153, v59
	v_mul_f32_e32 v56, v158, v56
	v_mul_f32_e32 v57, v159, v57
	ds_read_b64_tr_b16 v[236:237], v166 offset:0xc0
	ds_read_b64_tr_b16 v[238:239], v166 offset:0x11c0
	v_mfma_f32_16x16x32_bf16 v[52:55], v[240:243], v[140:143], v[52:55]
	ds_read_b64_tr_b16 v[240:241], v166 offset:0x44c0
	ds_read_b64_tr_b16 v[242:243], v166 offset:0x55c0
	v_mfma_f32_16x16x32_bf16 v[48:51], v[244:247], v[136:139], v[48:51]
	ds_read_b64_tr_b16 v[244:245], v166 offset:0xe0
	ds_read_b64_tr_b16 v[246:247], v166 offset:0x11e0
	v_mfma_f32_16x16x32_bf16 v[48:51], v[248:251], v[140:143], v[48:51]
	ds_read_b64_tr_b16 v[248:249], v166 offset:0x44e0
	ds_read_b64_tr_b16 v[250:251], v166 offset:0x55e0
	s_waitcnt lgkmcnt(8)
	v_mfma_f32_16x16x32_bf16 v[60:63], v[216:219], v[136:139], v[60:63]
	v_mul_f32_e32 v70, v152, v70
	v_mul_f32_e32 v71, v153, v71
	v_mul_f32_e32 v68, v158, v68
	v_mul_f32_e32 v69, v159, v69
	v_mul_f32_e32 v66, v152, v66
	v_mul_f32_e32 v67, v153, v67
	v_mul_f32_e32 v64, v158, v64
	v_mul_f32_e32 v65, v159, v65
	ds_read_b64_tr_b16 v[216:217], v166 offset:0x100
	ds_read_b64_tr_b16 v[218:219], v166 offset:0x1200
	v_mfma_f32_16x16x32_bf16 v[60:63], v[220:223], v[140:143], v[60:63]
	ds_read_b64_tr_b16 v[220:221], v166 offset:0x4500
	ds_read_b64_tr_b16 v[222:223], v166 offset:0x5600
	v_mfma_f32_16x16x32_bf16 v[56:59], v[224:227], v[136:139], v[56:59]
	ds_read_b64_tr_b16 v[224:225], v166 offset:0x120
	ds_read_b64_tr_b16 v[226:227], v166 offset:0x1220
	v_mfma_f32_16x16x32_bf16 v[56:59], v[232:235], v[140:143], v[56:59]
	ds_read_b64_tr_b16 v[232:233], v166 offset:0x4520
	ds_read_b64_tr_b16 v[234:235], v166 offset:0x5620
	s_waitcnt lgkmcnt(8)
	v_mfma_f32_16x16x32_bf16 v[68:71], v[236:239], v[136:139], v[68:71]
	v_mul_f32_e32 v78, v152, v78
	v_mul_f32_e32 v79, v153, v79
	v_mul_f32_e32 v76, v158, v76
	v_mul_f32_e32 v77, v159, v77
	v_mul_f32_e32 v74, v152, v74
	v_mul_f32_e32 v75, v153, v75
	v_mul_f32_e32 v72, v158, v72
	v_mul_f32_e32 v73, v159, v73
	ds_read_b64_tr_b16 v[236:237], v166 offset:0x140
	ds_read_b64_tr_b16 v[238:239], v166 offset:0x1240
	v_mfma_f32_16x16x32_bf16 v[68:71], v[240:243], v[140:143], v[68:71]
	ds_read_b64_tr_b16 v[240:241], v166 offset:0x4540
	ds_read_b64_tr_b16 v[242:243], v166 offset:0x5640
	v_mfma_f32_16x16x32_bf16 v[64:67], v[244:247], v[136:139], v[64:67]
	ds_read_b64_tr_b16 v[244:245], v166 offset:0x160
	ds_read_b64_tr_b16 v[246:247], v166 offset:0x1260
	v_mfma_f32_16x16x32_bf16 v[64:67], v[248:251], v[140:143], v[64:67]
	ds_read_b64_tr_b16 v[248:249], v166 offset:0x4560
	ds_read_b64_tr_b16 v[250:251], v166 offset:0x5660
	s_waitcnt lgkmcnt(8)
; #define MFMA16(a, b, c) __builtin_amdgcn_mfma_f32_16x16x32_bf16((a), (b), (c), 0, 0, 0)
; #define RT_CB() do { asm volatile("" ::: "memory"); __builtin_amdgcn_sched_barrier(0); } while (0)
; #define RT_LGKM(n) do { asm volatile("s_waitcnt lgkmcnt(" #n ")" ::: "memory"); __builtin_amdgcn_sched_barrier(0); } while (0)
; template <int FWD, class BarrierFn>
; DI void scan2_dir(const bf16_t* __restrict__ Qg, const bf16_t* __restrict__ Kg, bf16_t* Vg, bf16_t* Tg, bf16_t* TCB, float* stats, int b, int h, int sl, float lg, char* lds, const BarrierFn& gbar) {
;     ...
;             kt_load<2>(kb2, kb_tr);  RT_LGKM(8); kt_mma(st[0], st[1], ka, vz0, vz1);
;             kt_load<4>(ka, kb_tr);   RT_LGKM(8); kt_mma(st[2], st[3], kb2, vz0, vz1);
;             kt_load<6>(kb2, kb_tr);  RT_LGKM(8); kt_mma(st[4], st[5], ka, vz0, vz1);
;             kt_load<8>(ka, kb_tr);   RT_LGKM(8); kt_mma(st[6], st[7], kb2, vz0, vz1);
;             kt_load<10>(kb2, kb_tr); RT_LGKM(8); kt_mma(st[8], st[9], ka, vz0, vz1);
;             kt_load<12>(ka, kb_tr);  RT_LGKM(8); kt_mma(st[10], st[11], kb2, vz0, vz1);
;             kt_load<14>(kb2, kb_tr); RT_LGKM(8); kt_mma(st[12], st[13], ka, vz0, vz1);
;             RT_LGKM(0); kt_mma(st[14], st[15], kb2, vz0, vz1);
;         }
;         __syncthreads();
;         {
;             bf16x8 pa[4], pb[4];
; #pragma unroll
;             for (int nt = 0; nt < 4; ++nt) { pa[nt] = *(const bf16x8*)(p_rd + nt * 16 * PRS); pb[nt] = *(const bf16x8*)(p_rd + nt * 16 * PRS + 64); }
;             RT_CB();
; #pragma unroll
;             for (int nt = 0; nt < 4; ++nt) { o[nt] = MFMA16(pa[nt], vf0, o[nt]); o[nt] = MFMA16(pb[nt], vf1, o[nt]); }
;         }
; #pragma unroll
;         for (int nt = 0; nt < 4; ++nt)
; #pragma unroll
;             for (int r = 0; r < 4; ++r) stg_w[(nt * 16 + r) * S2RS] = o[nt][r];
;         __syncthreads();
;         if (step + 1 < 68) R2_WRITE();
	v_mfma_f32_16x16x32_bf16 v[76:79], v[216:219], v[136:139], v[76:79]
	v_mul_f32_e32 v86, v152, v86
	v_mul_f32_e32 v87, v153, v87
	v_mul_f32_e32 v84, v158, v84
	v_mul_f32_e32 v85, v159, v85
	v_mul_f32_e32 v82, v152, v82
	v_mul_f32_e32 v83, v153, v83
	v_mul_f32_e32 v80, v158, v80
	v_mul_f32_e32 v81, v159, v81
	ds_read_b64_tr_b16 v[216:217], v166 offset:0x180
	ds_read_b64_tr_b16 v[218:219], v166 offset:0x1280
	v_mfma_f32_16x16x32_bf16 v[76:79], v[220:223], v[140:143], v[76:79]
	ds_read_b64_tr_b16 v[220:221], v166 offset:0x4580
	ds_read_b64_tr_b16 v[222:223], v166 offset:0x5680
	v_mfma_f32_16x16x32_bf16 v[72:75], v[224:227], v[136:139], v[72:75]
	ds_read_b64_tr_b16 v[224:225], v166 offset:0x1a0
	ds_read_b64_tr_b16 v[226:227], v166 offset:0x12a0
	v_mfma_f32_16x16x32_bf16 v[72:75], v[232:235], v[140:143], v[72:75]
	ds_read_b64_tr_b16 v[232:233], v166 offset:0x45a0
	ds_read_b64_tr_b16 v[234:235], v166 offset:0x56a0
	s_waitcnt lgkmcnt(8)
	v_mfma_f32_16x16x32_bf16 v[84:87], v[236:239], v[136:139], v[84:87]
	v_mul_f32_e32 v94, v152, v94
	v_mul_f32_e32 v95, v153, v95
	v_mul_f32_e32 v92, v158, v92
	v_mul_f32_e32 v93, v159, v93
	v_mul_f32_e32 v102, v152, v102
	v_mul_f32_e32 v103, v153, v103
	v_mul_f32_e32 v100, v158, v100
	v_mul_f32_e32 v101, v159, v101
	ds_read_b64_tr_b16 v[236:237], v166 offset:0x1c0
	ds_read_b64_tr_b16 v[238:239], v166 offset:0x12c0
	v_mfma_f32_16x16x32_bf16 v[84:87], v[240:243], v[140:143], v[84:87]
	ds_read_b64_tr_b16 v[240:241], v166 offset:0x45c0
	ds_read_b64_tr_b16 v[242:243], v166 offset:0x56c0
	v_mfma_f32_16x16x32_bf16 v[80:83], v[244:247], v[136:139], v[80:83]
	ds_read_b64_tr_b16 v[244:245], v166 offset:0x1e0
	ds_read_b64_tr_b16 v[246:247], v166 offset:0x12e0
	v_mfma_f32_16x16x32_bf16 v[80:83], v[248:251], v[140:143], v[80:83]
	ds_read_b64_tr_b16 v[248:249], v166 offset:0x45e0
	ds_read_b64_tr_b16 v[250:251], v166 offset:0x56e0
	s_waitcnt lgkmcnt(8)
	v_mfma_f32_16x16x32_bf16 v[92:95], v[216:219], v[136:139], v[92:95]
	v_mul_f32_e32 v98, v152, v98
	v_mul_f32_e32 v99, v153, v99
	v_mul_f32_e32 v96, v158, v96
	v_mul_f32_e32 v97, v159, v97
	v_mul_f32_e32 v90, v152, v90
	v_mul_f32_e32 v91, v153, v91
	v_mul_f32_e32 v88, v158, v88
	v_mul_f32_e32 v89, v159, v89
	s_waitcnt lgkmcnt(0)
	v_mfma_f32_16x16x32_bf16 v[100:103], v[224:227], v[136:139], v[100:103]
	v_mfma_f32_16x16x32_bf16 v[92:95], v[220:223], v[140:143], v[92:95]
	v_mfma_f32_16x16x32_bf16 v[100:103], v[232:235], v[140:143], v[100:103]
	v_mfma_f32_16x16x32_bf16 v[96:99], v[236:239], v[136:139], v[96:99]
	s_waitcnt lgkmcnt(0)
	s_barrier
	v_mfma_f32_16x16x32_bf16 v[88:91], v[244:247], v[136:139], v[88:91]
	v_mfma_f32_16x16x32_bf16 v[96:99], v[240:243], v[140:143], v[96:99]
	v_mfma_f32_16x16x32_bf16 v[88:91], v[248:251], v[140:143], v[88:91]
	ds_read_b128 v[136:139], v215
	ds_read_b128 v[140:143], v215 offset:64
	ds_read_b128 v[216:219], v215 offset:2304
	ds_read_b128 v[220:223], v215 offset:2368
	ds_read_b128 v[224:227], v215 offset:4608
	ds_read_b128 v[232:235], v215 offset:4672
	ds_read_b128 v[236:239], v215 offset:6912
	ds_read_b128 v[240:243], v215 offset:6976
	s_waitcnt lgkmcnt(7)
	v_mfma_f32_16x16x32_bf16 v[132:135], v[136:139], v[120:123], v[132:135]
	s_andn2_b64 vcc, exec, s[0:1]
	s_waitcnt lgkmcnt(5)
	v_mfma_f32_16x16x32_bf16 v[128:131], v[216:219], v[120:123], v[128:131]
	v_mfma_f32_16x16x32_bf16 v[132:135], v[140:143], v[124:127], v[132:135]
	s_waitcnt lgkmcnt(3)
	v_mfma_f32_16x16x32_bf16 v[116:119], v[224:227], v[120:123], v[116:119]
	v_mfma_f32_16x16x32_bf16 v[128:131], v[220:223], v[124:127], v[128:131]
	s_nop 4
	ds_write2_b32 v206, v132, v133 offset1:132
	v_add_u32_e32 v132, 0x400, v206
	ds_write2_b32 v132, v134, v135 offset0:8 offset1:140
	s_waitcnt lgkmcnt(3)
	v_mfma_f32_16x16x32_bf16 v[112:115], v[236:239], v[120:123], v[112:115]
	v_add_u32_e32 v132, 0x2000, v206
	ds_write2_b32 v132, v128, v129 offset0:64 offset1:196
	v_add_u32_e32 v128, 0x2400, v206
	v_mfma_f32_16x16x32_bf16 v[116:119], v[232:235], v[124:127], v[116:119]
	ds_write2_b32 v128, v130, v131 offset0:72 offset1:204
	v_add_u32_e32 v128, 0x4200, v206
	s_waitcnt lgkmcnt(4)
	v_mfma_f32_16x16x32_bf16 v[112:115], v[240:243], v[124:127], v[112:115]
	s_nop 3
	ds_write2_b32 v128, v116, v117 offset1:132
	v_add_u32_e32 v116, 0x4600, v206
	ds_write2_b32 v116, v118, v119 offset0:8 offset1:140
	v_add_u32_e32 v116, 0x6200, v206
	ds_write2_b32 v116, v112, v113 offset0:64 offset1:196
	v_add_u32_e32 v112, 0x6600, v206
	ds_write2_b32 v112, v114, v115 offset0:72 offset1:204
	s_waitcnt lgkmcnt(0)
	s_barrier
	ds_read_b128 v[112:115], v207
	ds_read_b128 v[120:123], v207 offset:16
	s_cbranch_vccnz .Lscan0_skipw
	s_waitcnt vmcnt(9)
	ds_write_b128 v198, v[0:3]
	s_waitcnt vmcnt(8)
	ds_write_b128 v199, v[4:7] offset:33792
	s_waitcnt vmcnt(7)
	ds_write_b128 v200, v[8:11]
	s_waitcnt vmcnt(6)
	ds_write_b128 v201, v[12:15] offset:33792
	s_waitcnt vmcnt(5)
	ds_write_b128 v202, v[16:19]
	s_waitcnt vmcnt(4)
	ds_write_b128 v203, v[20:23] offset:33792
	s_waitcnt vmcnt(3)
	ds_write_b128 v204, v[24:27]
	s_waitcnt vmcnt(2)
	ds_write_b128 v205, v[28:31] offset:33792
	s_waitcnt vmcnt(1)
	ds_write_b128 v208, v[32:35]
	s_waitcnt vmcnt(0)
	ds_write_b128 v209, v[36:39]
; DI float bflo(unsigned w) { return __uint_as_float(w << 16); }
; DI float bfhi(unsigned w) { return __uint_as_float(w & 0xffff0000u); }
; DI void store8(bf16_t* p, f32x4 a, f32x4 b) { u32x4 w = {cvt_pk_bf16(a[0], a[1]), cvt_pk_bf16(a[2], a[3]), cvt_pk_bf16(b[0], b[1]), cvt_pk_bf16(b[2], b[3])}; *(u32x4*)p = w; }
; template <int FWD, class BarrierFn>
; DI void scan2_dir(const bf16_t* __restrict__ Qg, const bf16_t* __restrict__ Kg, bf16_t* Vg, bf16_t* Tg, bf16_t* TCB, float* stats, int b, int h, int sl, float lg, char* lds, const BarrierFn& gbar) {
;     ...
;         {
;             bf16_t* dst = (fin ? Vg : ((!FWD && step < 4) ? TCB - (size_t)TL * 2048 : Tg));
; #pragma unroll
;             for (int hf = 0; hf < 2; ++hf) {
;                 const float* sr = stg_r + hf * 32 * S2RS; const float xi = hf ? xi1 : xi0;
;                 f32x4 b0 = *(const f32x4*)sr * xi, b1 = *(const f32x4*)(sr + 4) * xi;
;                 if (fin) { const bf16x8 tvv = hf ? tv1 : tv0; const u32x4 ow = *reinterpret_cast<const u32x4*>(&tvv);
;                     b0[0] += bflo(ow[0]); b0[1] += bfhi(ow[0]); b0[2] += bflo(ow[1]); b0[3] += bfhi(ow[1]); b1[0] += bflo(ow[2]); b1[1] += bfhi(ow[2]); b1[2] += bflo(ow[3]); b1[3] += bfhi(ow[3]); }
;                 const size_t row = (size_t)(rb + srow + 32 * hf);
;                 store8(dst + row * 2048 + vcol + scp * 8, b0, b1);
;                 if (fin) {
;                     float sm = (b0[0] + b0[1]) + (b0[2] + b0[3]) + (b1[0] + b1[1]) + (b1[2] + b1[3]);
;                     float sq = (b0[0] * b0[0] + b0[1] * b0[1]) + (b0[2] * b0[2] + b0[3] * b0[3]) + (b1[0] * b1[0] + b1[1] * b1[1]) + (b1[2] * b1[2] + b1[3] * b1[3]);
; #pragma unroll
;                     for (int o_ = 1; o_ < 16; o_ <<= 1) { sm += __shfl_xor(sm, o_, 64); sq += __shfl_xor(sq, o_, 64); }
;                     if (scp == 0) { float* sp = stats + (row * 4 + h) * 2; unsafeAtomicAdd(sp, sm); unsafeAtomicAdd(sp + 1, sq); }
;                 }
.LBB0_445:
	s_andn2_b64 vcc, exec, s[72:73]
	s_waitcnt lgkmcnt(11)
	v_pk_mul_f32 v[116:117], v[160:161], v[114:115]
	s_waitcnt lgkmcnt(10)
	v_pk_mul_f32 v[114:115], v[148:149], v[120:121]
	v_cndmask_b32_e64 v120, 0, 1, s[72:73]
	v_pk_mul_f32 v[118:119], v[148:149], v[112:113]
	v_pk_mul_f32 v[112:113], v[160:161], v[122:123]
	v_cmp_ne_u32_e64 s[0:1], 1, v120
	s_cbranch_vccnz .LBB0_447
	s_waitcnt vmcnt(1)
	v_lshlrev_b32_e32 v120, 16, v108
	v_and_b32_e32 v121, 0xffff0000, v108
	v_lshlrev_b32_e32 v108, 16, v109
	v_and_b32_e32 v109, 0xffff0000, v109
	v_pk_add_f32 v[116:117], v[116:117], v[108:109]
	v_lshlrev_b32_e32 v108, 16, v110
	v_and_b32_e32 v109, 0xffff0000, v110
	v_pk_add_f32 v[114:115], v[114:115], v[108:109]
	v_lshlrev_b32_e32 v108, 16, v111
	v_and_b32_e32 v109, 0xffff0000, v111
	v_pk_add_f32 v[118:119], v[118:119], v[120:121]
	v_pk_add_f32 v[112:113], v[112:113], v[108:109]
.LBB0_447:
	s_and_b64 s[46:47], s[70:71], exec
	v_readlane_b32 s46, v254, 32
	s_cselect_b32 s70, s46, s58
	v_readlane_b32 s46, v254, 33
	s_cselect_b32 s71, s46, s59
	s_and_b64 s[46:47], s[72:73], exec
	s_cselect_b32 s47, s97, s71
	s_cselect_b32 s46, s96, s70
	s_lshl_b32 s70, s63, 1
	s_add_u32 s46, s46, s70
	s_addc_u32 s47, s47, 0
	s_waitcnt vmcnt(1)
	v_lshl_add_u64 v[108:109], s[46:47], 0, v[180:181]
	v_lshlrev_b64 v[110:111], 12, v[164:165]
	v_lshl_add_u64 v[110:111], v[108:109], 0, v[110:111]
	s_and_b64 vcc, exec, s[0:1]
	v_cvt_pk_bf16_f32 v120, v118, v119
	v_cvt_pk_bf16_f32 v121, v116, v117
	v_cvt_pk_bf16_f32 v122, v114, v115
	v_cvt_pk_bf16_f32 v123, v112, v113
	global_store_dwordx4 v[110:111], v[120:123], off
	s_cbranch_vccnz .LBB0_451
	v_add_f32_e32 v110, v118, v119
	v_add_f32_e32 v111, v116, v117
	v_add_f32_e32 v110, v110, v111
	v_add_f32_e32 v111, v114, v115
	v_add_f32_e32 v110, v110, v111
	v_add_f32_e32 v111, v112, v113
	v_add_f32_e32 v110, v111, v110
	v_mul_f32_e32 v111, v119, v119
	v_mul_f32_e32 v117, v117, v117
	v_fmac_f32_e32 v111, v118, v118
	v_fmac_f32_e32 v117, v116, v116
	v_mul_f32_e32 v115, v115, v115
	v_add_f32_e32 v111, v111, v117
	v_fmac_f32_e32 v115, v114, v114
	v_mul_f32_e32 v113, v113, v113
	v_add_f32_e32 v111, v111, v115
	v_fmac_f32_e32 v113, v112, v112
	v_add_f32_e32 v111, v113, v111
	s_nop 1
	v_add_f32_dpp v110, v110, v110 quad_perm:[1,0,3,2] row_mask:0xf bank_mask:0xf
	v_add_f32_dpp v111, v111, v111 quad_perm:[1,0,3,2] row_mask:0xf bank_mask:0xf
	s_nop 1
	v_add_f32_dpp v110, v110, v110 quad_perm:[2,3,0,1] row_mask:0xf bank_mask:0xf
	v_add_f32_dpp v111, v111, v111 quad_perm:[2,3,0,1] row_mask:0xf bank_mask:0xf
	s_nop 1
	v_add_f32_dpp v110, v110, v110 row_half_mirror row_mask:0xf bank_mask:0xf
	v_add_f32_dpp v111, v111, v111 row_half_mirror row_mask:0xf bank_mask:0xf
	s_nop 1
	v_add_f32_dpp v112, v110, v110 row_mirror row_mask:0xf bank_mask:0xf
	v_add_f32_dpp v113, v111, v111 row_mirror row_mask:0xf bank_mask:0xf
	s_and_saveexec_b64 s[46:47], s[4:5]
	s_cbranch_execz .LBB0_450
	v_readlane_b32 s70, v254, 23
	v_lshlrev_b64 v[110:111], 5, v[164:165]
	v_readlane_b32 s71, v254, 24
	s_nop 1
	v_lshl_add_u64 v[110:111], s[70:71], 0, v[110:111]
	global_atomic_add_f32 v[110:111], v112, off
	global_atomic_add_f32 v[110:111], v113, off offset:4
